# norm loops fix + scans: state waves L2-touch the Q/K/V lines two chunks ahead (score waves then hit L2)
# speedup vs baseline: 1.0906x; 1.0906x over previous
.LBB0_414:
	v_cvt_f32_ubyte0_e32 v2, s9
	v_sub_f32_e32 v2, 0xc0a00000, v2
	v_cmp_gt_f32_e32 vcc, s42, v2
	s_and_b64 s[6:7], vcc, exec
	s_cselect_b32 s0, 0xffffffc0, 0
	v_cndmask_b32_e32 v3, 0, v250, vcc
	v_add_f32_e32 v2, v2, v3
	v_exp_f32_e32 v2, v2
	s_nop 0
	v_ldexp_f32 v18, v2, s0
	v_sub_f32_e32 v4, 1.0, v18
	v_cvt_f64_f32_e32 v[2:3], v4
	v_frexp_exp_i32_f64_e32 v2, v[2:3]
	v_frexp_mant_f32_e32 v3, v4
	s_mov_b32 s0, 0x3f2aaaab
	v_cmp_gt_f32_e32 vcc, s0, v3
	v_add_f32_e32 v6, -1.0, v4
	v_sub_f32_e64 v7, -v18, v6
	v_subbrev_co_u32_e32 v3, vcc, 0, v2, vcc
	v_cvt_f32_i32_e32 v2, v3
	v_sub_u32_e32 v3, 0, v3
	v_ldexp_f32 v5, v4, v3
	v_sub_f32_e32 v4, v6, v4
	v_add_f32_e32 v4, 1.0, v4
	v_add_f32_e32 v9, -1.0, v5
	v_add_f32_e32 v4, v7, v4
	v_ldexp_f32 v3, v4, v3
	v_add_f32_e32 v4, 1.0, v9
	v_sub_f32_e32 v4, v5, v4
	v_add_f32_e32 v10, v3, v4
	v_add_f32_e32 v4, 1.0, v5
	v_add_f32_e32 v6, -1.0, v4
	v_sub_f32_e32 v5, v5, v6
	v_add_f32_e32 v3, v3, v5
	v_add_f32_e32 v12, v4, v3
	v_rcp_f32_e32 v13, v12
	v_add_f32_e32 v5, v9, v10
	v_sub_f32_e32 v4, v12, v4
	v_sub_f32_e32 v3, v3, v4
	v_mul_f32_e32 v14, v5, v13
	v_mul_f32_e32 v6, v12, v14
	v_fma_f32 v8, v14, v12, -v6
	v_fmac_f32_e32 v8, v14, v3
	v_add_f32_e32 v4, v6, v8
	v_sub_f32_e32 v7, v5, v4
	v_sub_f32_e32 v9, v5, v9
	v_sub_f32_e32 v15, v10, v9
	v_pk_add_f32 v[10:11], v[4:5], v[6:7] neg_lo:[0,1] neg_hi:[0,1]
	v_mov_b32_e32 v9, v4
	v_pk_add_f32 v[4:5], v[10:11], v[8:9] neg_lo:[0,1] neg_hi:[0,1]
	s_mov_b32 s0, 0x3f317218
	v_add_f32_e32 v5, v15, v5
	v_add_f32_e32 v10, v4, v5
	v_add_f32_e32 v5, v7, v10
	v_mul_f32_e32 v4, v13, v5
	v_add_f32_e32 v15, v14, v4
	v_sub_f32_e32 v6, v15, v14
	v_mul_f32_e32 v8, v12, v4
	v_sub_f32_e32 v14, v4, v6
	v_fma_f32 v6, v4, v12, -v8
	v_fmac_f32_e32 v6, v4, v3
	v_add_f32_e32 v4, v8, v6
	v_sub_f32_e32 v9, v5, v4
	v_sub_f32_e32 v3, v7, v5
	v_add_f32_e32 v3, v10, v3
	v_pk_add_f32 v[10:11], v[4:5], v[8:9] neg_lo:[0,1] neg_hi:[0,1]
	v_mov_b32_e32 v7, v4
	v_pk_add_f32 v[4:5], v[10:11], v[6:7] neg_lo:[0,1] neg_hi:[0,1]
	v_mov_b32_e32 v8, 0x3ecc95a3
	v_add_f32_e32 v3, v3, v5
	v_add_f32_e32 v3, v4, v3
	v_add_f32_e32 v3, v9, v3
	v_mul_f32_e32 v3, v13, v3
	v_add_f32_e32 v4, v14, v3
	v_add_f32_e32 v6, v15, v4
	v_mul_f32_e32 v7, v6, v6
	v_fmamk_f32 v8, v7, 0x3e9b6dac, v8
	v_ldexp_f32 v5, v6, 1
	v_mul_f32_e32 v3, v6, v7
	v_fmaak_f32 v217, v7, v8, 0x3f2aaada
	v_sub_f32_e32 v6, v6, v15
	v_sub_f32_e32 v4, v4, v6
	v_pk_mul_f32 v[6:7], v[2:3], v[216:217]
	v_ldexp_f32 v8, v4, 1
	v_fma_f32 v4, v2, s0, -v6
	v_fmac_f32_e32 v4, 0xb102e308, v2
	v_pk_add_f32 v[2:3], v[6:7], v[4:5]
	v_cmp_nlt_f32_e32 vcc, 1.0, v18
	v_sub_f32_e32 v5, v3, v5
	v_sub_f32_e32 v5, v7, v5
	v_add_f32_e32 v9, v8, v5
	v_mov_b32_e32 v8, v6
	v_pk_add_f32 v[6:7], v[2:3], v[6:7] neg_lo:[0,1] neg_hi:[0,1]
	v_pk_add_f32 v[10:11], v[2:3], v[8:9]
	v_mov_b32_e32 v5, v2
	v_mov_b32_e32 v7, v11
	v_pk_add_f32 v[12:13], v[4:5], v[6:7] neg_lo:[0,1] neg_hi:[0,1]
	v_pk_add_f32 v[4:5], v[4:5], v[6:7]
	v_mov_b32_e32 v16, v3
	v_pk_add_f32 v[6:7], v[4:5], v[2:3] op_sel:[1,0] op_sel_hi:[0,1] neg_lo:[0,1] neg_hi:[0,1]
	v_pk_add_f32 v[14:15], v[10:11], v[6:7] op_sel_hi:[1,0] neg_lo:[0,1] neg_hi:[0,1]
	v_mov_b32_e32 v10, v11
	v_mov_b32_e32 v11, v5
	v_mov_b32_e32 v17, v6
	v_pk_add_f32 v[6:7], v[10:11], v[16:17] neg_lo:[0,1] neg_hi:[0,1]
	v_mov_b32_e32 v8, v9
	v_mov_b32_e32 v9, v2
	v_pk_add_f32 v[2:3], v[8:9], v[6:7] neg_lo:[0,1] neg_hi:[0,1]
	v_mov_b32_e32 v14, v12
	v_pk_add_f32 v[6:7], v[14:15], v[2:3]
	v_mov_b32_e32 v13, v5
	v_pk_add_f32 v[8:9], v[6:7], v[6:7] op_sel:[0,1] op_sel_hi:[1,0]
	s_mov_b32 s0, 0x33800000
	v_pk_add_f32 v[4:5], v[4:5], v[8:9] op_sel:[1,0] op_sel_hi:[0,1]
	v_mov_b32_e32 v7, v4
	v_pk_add_f32 v[10:11], v[6:7], v[12:13] neg_lo:[0,1] neg_hi:[0,1]
	v_mov_b32_e32 v3, v8
	v_sub_f32_e32 v5, v6, v10
	v_pk_add_f32 v[2:3], v[2:3], v[10:11] neg_lo:[0,1] neg_hi:[0,1]
	v_sub_f32_e32 v5, v12, v5
	v_add_f32_e32 v2, v2, v5
	v_add_f32_e32 v2, v2, v3
	v_add_f32_e32 v2, v4, v2
	v_cndmask_b32_e32 v2, v251, v2, vcc
	v_cmp_neq_f32_e32 vcc, 1.0, v18
	s_nop 1
	v_cndmask_b32_e32 v2, v252, v2, vcc
	v_cmp_gt_f32_e32 vcc, s0, v18
	s_nop 1
	v_cndmask_b32_e64 v2, v2, -v18, vcc
	v_mul_f32_e32 v2, 0x3fb8aa3b, v2
	v_mul_f32_e32 v3, 0x42800000, v2
	v_cmp_gt_f32_e32 vcc, s42, v3
	s_and_b64 s[6:7], vcc, exec
	s_cselect_b32 s0, 0xffffffc0, 0
	v_cndmask_b32_e32 v3, 0, v250, vcc
	v_fmac_f32_e32 v3, 0x42800000, v2
	v_exp_f32_e32 v3, v3
	s_lshl_b32 s6, s10, 11
	s_ashr_i32 s7, s6, 31
	s_lshl_b64 s[6:7], s[6:7], 13
	v_ldexp_f32 v218, v3, s0
	s_lshl_b32 s12, s8, 5
	s_and_b32 s0, s84, 0x1c00
	s_ashr_i32 s13, s12, 31
	s_or_b32 s6, s6, s0
	s_andn2_b32 s11, s11, 63
	s_or_b64 s[6:7], s[6:7], s[60:61]
	s_lshl_b64 s[12:13], s[12:13], 1
	s_add_u32 s6, s6, s12
	v_mov_b32_e32 v2, 0
	v_or_b32_e32 v3, s11, v224
	s_addc_u32 s7, s7, s13
	v_mov_b32_e32 v220, v218
	v_mov_b32_e32 v221, v218
	v_lshl_add_u64 v[222:223], v[212:213], 0, s[6:7]
	s_mov_b64 s[6:7], 0
	v_add_u32_e32 v215, v226, v3
	v_mov_b32_e32 v3, v2
	v_mov_b32_e32 v4, v2
	v_mov_b32_e32 v5, v2
	v_mov_b32_e32 v30, v2
	v_mov_b32_e32 v31, v2
	v_mov_b32_e32 v32, v2
	v_mov_b32_e32 v33, v2
	v_mov_b32_e32 v34, v2
	v_mov_b32_e32 v35, v2
	v_mov_b32_e32 v36, v2
	v_mov_b32_e32 v37, v2
	v_mov_b32_e32 v38, v2
	v_mov_b32_e32 v39, v2
	v_mov_b32_e32 v40, v2
	v_mov_b32_e32 v41, v2
	v_mov_b32_e32 v58, v2
	v_mov_b32_e32 v59, v2
	v_mov_b32_e32 v60, v2
	v_mov_b32_e32 v61, v2
	v_mov_b32_e32 v62, v2
	v_mov_b32_e32 v63, v2
	v_mov_b32_e32 v64, v2
	v_mov_b32_e32 v65, v2
	v_mov_b32_e32 v6, v2
	v_mov_b32_e32 v7, v2
	v_mov_b32_e32 v8, v2
	v_mov_b32_e32 v9, v2
	v_mov_b32_e32 v10, v2
	v_mov_b32_e32 v11, v2
	v_mov_b32_e32 v12, v2
	v_mov_b32_e32 v13, v2
	v_mov_b32_e32 v14, v2
	v_mov_b32_e32 v15, v2
	v_mov_b32_e32 v16, v2
	v_mov_b32_e32 v17, v2
	v_mov_b32_e32 v18, v2
	v_mov_b32_e32 v19, v2
	v_mov_b32_e32 v20, v2
	v_mov_b32_e32 v21, v2
	v_mov_b32_e32 v22, v2
	v_mov_b32_e32 v23, v2
	v_mov_b32_e32 v24, v2
	v_mov_b32_e32 v25, v2
	v_mov_b32_e32 v26, v2
	v_mov_b32_e32 v27, v2
	v_mov_b32_e32 v28, v2
	v_mov_b32_e32 v29, v2
	v_mov_b32_e32 v42, v2
	v_mov_b32_e32 v43, v2
	v_mov_b32_e32 v44, v2
	v_mov_b32_e32 v45, v2
	v_mov_b32_e32 v46, v2
	v_mov_b32_e32 v47, v2
	v_mov_b32_e32 v48, v2
	v_mov_b32_e32 v49, v2
	v_mov_b32_e32 v50, v2
	v_mov_b32_e32 v51, v2
	v_mov_b32_e32 v52, v2
	v_mov_b32_e32 v53, v2
	v_mov_b32_e32 v54, v2
	v_mov_b32_e32 v55, v2
	v_mov_b32_e32 v56, v2
	v_mov_b32_e32 v57, v2
	v_mov_b32_e32 v66, v2
	v_mov_b32_e32 v67, v2
	v_mov_b32_e32 v68, v2
	v_mov_b32_e32 v69, v2
	v_mov_b32_e32 v70, v2
	v_mov_b32_e32 v71, v2
	v_mov_b32_e32 v72, v2
	v_mov_b32_e32 v73, v2
	v_mov_b32_e32 v74, v2
	v_mov_b32_e32 v75, v2
	v_mov_b32_e32 v76, v2
	v_mov_b32_e32 v77, v2
	v_mov_b32_e32 v78, v2
	v_mov_b32_e32 v79, v2
	v_mov_b32_e32 v80, v2
	v_mov_b32_e32 v81, v2
	v_mov_b32_e32 v82, v2
	v_mov_b32_e32 v83, v2
	v_mov_b32_e32 v84, v2
	v_mov_b32_e32 v85, v2
	v_mov_b32_e32 v86, v2
	v_mov_b32_e32 v87, v2
	v_mov_b32_e32 v88, v2
	v_mov_b32_e32 v89, v2
	v_mov_b32_e32 v90, v2
	v_mov_b32_e32 v91, v2
	v_mov_b32_e32 v92, v2
	v_mov_b32_e32 v93, v2
	v_mov_b32_e32 v94, v2
	v_mov_b32_e32 v95, v2
	v_mov_b32_e32 v96, v2
	v_mov_b32_e32 v97, v2
	v_mov_b32_e32 v98, v2
	v_mov_b32_e32 v99, v2
	v_mov_b32_e32 v100, v2
	v_mov_b32_e32 v101, v2
	v_mov_b32_e32 v102, v2
	v_mov_b32_e32 v103, v2
	v_mov_b32_e32 v104, v2
	v_mov_b32_e32 v105, v2
	v_mov_b32_e32 v106, v2
	v_mov_b32_e32 v107, v2
	v_mov_b32_e32 v108, v2
	v_mov_b32_e32 v109, v2
	v_mov_b32_e32 v110, v2
	v_mov_b32_e32 v111, v2
	v_mov_b32_e32 v112, v2
	v_mov_b32_e32 v113, v2
	v_mov_b32_e32 v114, v2
	v_mov_b32_e32 v115, v2
	v_mov_b32_e32 v116, v2
	v_mov_b32_e32 v117, v2
	v_mov_b32_e32 v118, v2
	v_mov_b32_e32 v119, v2
	v_mov_b32_e32 v120, v2
	v_mov_b32_e32 v121, v2
	v_mov_b32_e32 v122, v2
	v_mov_b32_e32 v123, v2
	v_mov_b32_e32 v124, v2
	v_mov_b32_e32 v125, v2
	v_mov_b32_e32 v126, v2
	v_mov_b32_e32 v127, v2
	v_mov_b32_e32 v128, v2
	v_mov_b32_e32 v129, v2
	v_lshrrev_b32_e32 v206, 2, v0
	v_and_b32_e32 v208, 3, v0
	v_lshlrev_b32_e32 v207, 13, v206
	v_lshlrev_b32_e32 v206, 12, v206
	v_lshl_or_b32 v207, v208, 7, v207
	v_lshl_or_b32 v206, v208, 7, v206
.LBB0_415:
	s_waitcnt lgkmcnt(0)
	s_barrier
	s_lshl_b32 s98, s10, 23
	s_lshl_b32 s99, s9, 9
	s_add_i32 s98, s98, s99
	s_lshr_b32 s99, s6, 1
	s_add_i32 s98, s98, s99
	s_add_i32 s98, s98, 0x21f80000
	s_add_u32 s100, s48, s98
	s_addc_u32 s101, s49, 0
	s_nop 0
	global_load_dword v208, v206, s[100:101]
	s_add_u32 s100, s100, 0x4000000
	s_addc_u32 s101, s101, 0
	s_nop 0
	global_load_dword v208, v206, s[100:101]
	s_lshl_b32 s98, s10, 24
	s_lshl_b32 s99, s9, 10
	s_add_i32 s98, s98, s99
	s_add_i32 s98, s98, s60
	s_add_i32 s98, s98, s6
	s_add_i32 s98, s98, 0x2a000000
	s_add_u32 s100, s48, s98
	s_addc_u32 s101, s49, 0
	s_nop 0
	global_load_dword v208, v207, s[100:101]
	v_add_u32_e32 v198, 0x2000, v248
	v_add_u32_e32 v202, 0x4000, v248
	v_add_u32_e32 v217, 0x6000, v248
	ds_read2_b64 v[130:133], v248 offset1:4
	ds_read2_b64 v[134:137], v198 offset0:32 offset1:36
	ds_read2_b64 v[138:141], v202 offset0:64 offset1:68
	ds_read2_b64 v[142:145], v217 offset0:96 offset1:100
	ds_read2_b64 v[146:149], v248 offset0:8 offset1:12
	ds_read2_b64 v[150:153], v198 offset0:40 offset1:44
	ds_read2_b64 v[154:157], v202 offset0:72 offset1:76
	ds_read2_b64 v[158:161], v217 offset0:104 offset1:108
	v_cvt_pk_bf16_f32 v162, v126, v127
	v_cvt_pk_bf16_f32 v163, v128, v129
	v_cvt_pk_bf16_f32 v164, v118, v119
	v_cvt_pk_bf16_f32 v165, v120, v121
	v_cvt_pk_bf16_f32 v178, v122, v123
	v_cvt_pk_bf16_f32 v179, v124, v125
	v_cvt_pk_bf16_f32 v180, v114, v115
	v_cvt_pk_bf16_f32 v181, v116, v117
	s_waitcnt lgkmcnt(0)
	v_mfma_f32_16x16x32_bf16 v[166:169], v[162:165], v[130:133], 0
	v_mfma_f32_16x16x32_bf16 v[170:173], v[162:165], v[134:137], 0
	v_mfma_f32_16x16x32_bf16 v[174:177], v[162:165], v[138:141], 0
	v_mfma_f32_16x16x32_bf16 v[162:165], v[162:165], v[142:145], 0
	v_mfma_f32_16x16x32_bf16 v[130:133], v[178:181], v[130:133], 0
	v_mfma_f32_16x16x32_bf16 v[134:137], v[178:181], v[134:137], 0
	v_mfma_f32_16x16x32_bf16 v[138:141], v[178:181], v[138:141], 0
	v_mfma_f32_16x16x32_bf16 v[142:145], v[178:181], v[142:145], 0
	ds_read2_b64 v[178:181], v248 offset0:16 offset1:20
	ds_read2_b64 v[182:185], v198 offset0:48 offset1:52
	ds_read2_b64 v[186:189], v202 offset0:80 offset1:84
	ds_read2_b64 v[190:193], v217 offset0:112 offset1:116
	v_cvt_pk_bf16_f32 v194, v110, v111
	v_cvt_pk_bf16_f32 v195, v112, v113
	v_cvt_pk_bf16_f32 v196, v102, v103
	v_cvt_pk_bf16_f32 v197, v104, v105
	s_nop 1
	v_mfma_f32_16x16x32_bf16 v[166:169], v[194:197], v[146:149], v[166:169]
	v_mfma_f32_16x16x32_bf16 v[170:173], v[194:197], v[150:153], v[170:173]
	v_mfma_f32_16x16x32_bf16 v[174:177], v[194:197], v[154:157], v[174:177]
	v_mfma_f32_16x16x32_bf16 v[162:165], v[194:197], v[158:161], v[162:165]
	v_cvt_pk_bf16_f32 v194, v106, v107
	v_cvt_pk_bf16_f32 v195, v108, v109
	v_cvt_pk_bf16_f32 v196, v98, v99
	v_cvt_pk_bf16_f32 v197, v100, v101
	s_nop 1
	v_mfma_f32_16x16x32_bf16 v[130:133], v[194:197], v[146:149], v[130:133]
	v_mfma_f32_16x16x32_bf16 v[134:137], v[194:197], v[150:153], v[134:137]
	v_mfma_f32_16x16x32_bf16 v[138:141], v[194:197], v[154:157], v[138:141]
	v_mfma_f32_16x16x32_bf16 v[142:145], v[194:197], v[158:161], v[142:145]
	ds_read2_b64 v[146:149], v248 offset0:24 offset1:28
	ds_read2_b64 v[150:153], v198 offset0:56 offset1:60
	ds_read2_b64 v[154:157], v202 offset0:88 offset1:92
	ds_read2_b64 v[158:161], v217 offset0:120 offset1:124
	v_cvt_pk_bf16_f32 v194, v94, v95
	v_cvt_pk_bf16_f32 v195, v96, v97
	v_cvt_pk_bf16_f32 v196, v86, v87
	v_cvt_pk_bf16_f32 v197, v88, v89
	s_waitcnt lgkmcnt(0)
	s_nop 0
	v_mfma_f32_16x16x32_bf16 v[166:169], v[194:197], v[178:181], v[166:169]
	v_mfma_f32_16x16x32_bf16 v[170:173], v[194:197], v[182:185], v[170:173]
	v_mfma_f32_16x16x32_bf16 v[174:177], v[194:197], v[186:189], v[174:177]
	v_mfma_f32_16x16x32_bf16 v[162:165], v[194:197], v[190:193], v[162:165]
	v_cvt_pk_bf16_f32 v194, v90, v91
	v_cvt_pk_bf16_f32 v195, v92, v93
	v_cvt_pk_bf16_f32 v196, v82, v83
	v_cvt_pk_bf16_f32 v197, v84, v85
	s_nop 1
	v_mfma_f32_16x16x32_bf16 v[130:133], v[194:197], v[178:181], v[130:133]
	v_mfma_f32_16x16x32_bf16 v[134:137], v[194:197], v[182:185], v[134:137]
	v_mfma_f32_16x16x32_bf16 v[138:141], v[194:197], v[186:189], v[138:141]
	v_mfma_f32_16x16x32_bf16 v[142:145], v[194:197], v[190:193], v[142:145]
	ds_read2_b64 v[178:181], v248 offset0:32 offset1:36
	ds_read2_b64 v[182:185], v198 offset0:64 offset1:68
	ds_read2_b64 v[186:189], v202 offset0:96 offset1:100
	ds_read2_b64 v[190:193], v217 offset0:128 offset1:132
	v_cvt_pk_bf16_f32 v194, v78, v79
	v_cvt_pk_bf16_f32 v195, v80, v81
	v_cvt_pk_bf16_f32 v196, v70, v71
	v_cvt_pk_bf16_f32 v197, v72, v73
	s_nop 1
	v_mfma_f32_16x16x32_bf16 v[166:169], v[194:197], v[146:149], v[166:169]
	v_mfma_f32_16x16x32_bf16 v[170:173], v[194:197], v[150:153], v[170:173]
	v_mfma_f32_16x16x32_bf16 v[174:177], v[194:197], v[154:157], v[174:177]
	v_mfma_f32_16x16x32_bf16 v[162:165], v[194:197], v[158:161], v[162:165]
	v_cvt_pk_bf16_f32 v194, v74, v75
	v_cvt_pk_bf16_f32 v195, v76, v77
	v_cvt_pk_bf16_f32 v196, v66, v67
	v_cvt_pk_bf16_f32 v197, v68, v69
	s_nop 1
	v_mfma_f32_16x16x32_bf16 v[130:133], v[194:197], v[146:149], v[130:133]
	v_mfma_f32_16x16x32_bf16 v[134:137], v[194:197], v[150:153], v[134:137]
	v_mfma_f32_16x16x32_bf16 v[138:141], v[194:197], v[154:157], v[138:141]
	v_mfma_f32_16x16x32_bf16 v[142:145], v[194:197], v[158:161], v[142:145]
	ds_read2_b64 v[146:149], v248 offset0:40 offset1:44
	ds_read2_b64 v[150:153], v198 offset0:72 offset1:76
	ds_read2_b64 v[154:157], v202 offset0:104 offset1:108
	ds_read2_b64 v[158:161], v217 offset0:136 offset1:140
	v_cvt_pk_bf16_f32 v194, v54, v55
	v_cvt_pk_bf16_f32 v195, v56, v57
	v_cvt_pk_bf16_f32 v196, v46, v47
	v_cvt_pk_bf16_f32 v197, v48, v49
	s_waitcnt lgkmcnt(0)
	s_nop 0
	v_mfma_f32_16x16x32_bf16 v[166:169], v[194:197], v[178:181], v[166:169]
	v_mfma_f32_16x16x32_bf16 v[170:173], v[194:197], v[182:185], v[170:173]
	v_mfma_f32_16x16x32_bf16 v[174:177], v[194:197], v[186:189], v[174:177]
	v_mfma_f32_16x16x32_bf16 v[162:165], v[194:197], v[190:193], v[162:165]
	v_cvt_pk_bf16_f32 v194, v50, v51
	v_cvt_pk_bf16_f32 v195, v52, v53
	v_cvt_pk_bf16_f32 v196, v42, v43
	v_cvt_pk_bf16_f32 v197, v44, v45
	s_nop 1
	v_mfma_f32_16x16x32_bf16 v[130:133], v[194:197], v[178:181], v[130:133]
	v_mfma_f32_16x16x32_bf16 v[134:137], v[194:197], v[182:185], v[134:137]
	v_mfma_f32_16x16x32_bf16 v[138:141], v[194:197], v[186:189], v[138:141]
	v_mfma_f32_16x16x32_bf16 v[142:145], v[194:197], v[190:193], v[142:145]
	ds_read2_b64 v[178:181], v248 offset0:48 offset1:52
	ds_read2_b64 v[182:185], v198 offset0:80 offset1:84
	ds_read2_b64 v[186:189], v202 offset0:112 offset1:116
	ds_read2_b64 v[190:193], v217 offset0:144 offset1:148
	v_cvt_pk_bf16_f32 v194, v26, v27
	v_cvt_pk_bf16_f32 v195, v28, v29
	v_cvt_pk_bf16_f32 v196, v18, v19
	v_cvt_pk_bf16_f32 v197, v20, v21
	s_nop 1
	v_mfma_f32_16x16x32_bf16 v[166:169], v[194:197], v[146:149], v[166:169]
	v_mfma_f32_16x16x32_bf16 v[170:173], v[194:197], v[150:153], v[170:173]
	v_mfma_f32_16x16x32_bf16 v[174:177], v[194:197], v[154:157], v[174:177]
	v_mfma_f32_16x16x32_bf16 v[162:165], v[194:197], v[158:161], v[162:165]
	v_cvt_pk_bf16_f32 v194, v22, v23
	v_cvt_pk_bf16_f32 v195, v24, v25
	v_cvt_pk_bf16_f32 v196, v14, v15
	v_cvt_pk_bf16_f32 v197, v16, v17
	s_nop 1
	v_mfma_f32_16x16x32_bf16 v[130:133], v[194:197], v[146:149], v[130:133]
	v_mfma_f32_16x16x32_bf16 v[134:137], v[194:197], v[150:153], v[134:137]
	v_mfma_f32_16x16x32_bf16 v[138:141], v[194:197], v[154:157], v[138:141]
	v_mfma_f32_16x16x32_bf16 v[142:145], v[194:197], v[158:161], v[142:145]
	ds_read2_b64 v[194:197], v248 offset0:56 offset1:60
	ds_read2_b64 v[198:201], v198 offset0:88 offset1:92
	ds_read2_b64 v[202:205], v202 offset0:120 offset1:124
	ds_read2_b64 v[244:247], v217 offset0:152 offset1:156
	v_cvt_pk_bf16_f32 v146, v10, v11
	v_cvt_pk_bf16_f32 v147, v12, v13
	v_cvt_pk_bf16_f32 v148, v62, v63
	v_cvt_pk_bf16_f32 v149, v64, v65
	v_cvt_pk_bf16_f32 v158, v6, v7
	v_cvt_pk_bf16_f32 v159, v8, v9
	v_cvt_pk_bf16_f32 v160, v58, v59
	v_cvt_pk_bf16_f32 v161, v60, v61
	s_waitcnt lgkmcnt(0)
	v_mfma_f32_16x16x32_bf16 v[150:153], v[146:149], v[178:181], v[166:169]
	v_mfma_f32_16x16x32_bf16 v[154:157], v[146:149], v[182:185], v[170:173]
	v_mfma_f32_16x16x32_bf16 v[166:169], v[146:149], v[186:189], v[174:177]
	v_mfma_f32_16x16x32_bf16 v[146:149], v[146:149], v[190:193], v[162:165]
	v_mfma_f32_16x16x32_bf16 v[130:133], v[158:161], v[178:181], v[130:133]
	v_mfma_f32_16x16x32_bf16 v[134:137], v[158:161], v[182:185], v[134:137]
	v_mfma_f32_16x16x32_bf16 v[138:141], v[158:161], v[186:189], v[138:141]
	v_mfma_f32_16x16x32_bf16 v[142:145], v[158:161], v[190:193], v[142:145]
	s_waitcnt vmcnt(3)
	ds_read_b64_tr_b16 v[178:179], v225 offset:33792
	ds_read_b64_tr_b16 v[182:183], v225 offset:33824
	ds_read_b64_tr_b16 v[186:187], v225 offset:33856
	ds_read_b64_tr_b16 v[190:191], v225 offset:33888
	ds_read_b64_tr_b16 v[180:181], v225 offset:35968
	ds_read_b64_tr_b16 v[184:185], v225 offset:36000
	ds_read_b64_tr_b16 v[188:189], v225 offset:36032
	ds_read_b64_tr_b16 v[192:193], v225 offset:36064
	v_cvt_pk_bf16_f32 v162, v38, v39
	v_cvt_pk_bf16_f32 v163, v40, v41
	v_cvt_pk_bf16_f32 v164, v30, v31
	v_cvt_pk_bf16_f32 v165, v32, v33
	s_nop 1
	v_mfma_f32_16x16x32_bf16 v[158:161], v[162:165], v[194:197], v[150:153]
	v_mfma_f32_16x16x32_bf16 v[154:157], v[162:165], v[198:201], v[154:157]
	v_mfma_f32_16x16x32_bf16 v[150:153], v[162:165], v[202:205], v[166:169]
	v_mfma_f32_16x16x32_bf16 v[146:149], v[162:165], v[244:247], v[146:149]
	v_cvt_pk_bf16_f32 v162, v34, v35
	v_cvt_pk_bf16_f32 v163, v36, v37
	v_cvt_pk_bf16_f32 v164, v2, v3
	v_cvt_pk_bf16_f32 v165, v4, v5
	s_nop 1
	v_mfma_f32_16x16x32_bf16 v[174:177], v[162:165], v[194:197], v[130:133]
	v_mfma_f32_16x16x32_bf16 v[170:173], v[162:165], v[198:201], v[134:137]
	v_mfma_f32_16x16x32_bf16 v[166:169], v[162:165], v[202:205], v[138:141]
	v_mfma_f32_16x16x32_bf16 v[138:141], v[162:165], v[244:247], v[142:145]
	ds_read_b64_tr_b16 v[164:165], v215 offset:1152
	ds_read_b64_tr_b16 v[162:163], v215
	s_nop 0
	ds_read_b64_tr_b16 v[144:145], v215 offset:1184
	ds_read_b64_tr_b16 v[142:143], v215 offset:32
	ds_read_b64_tr_b16 v[130:131], v215 offset:9216
	ds_read_b64_tr_b16 v[132:133], v215 offset:10368
	ds_read_b64_tr_b16 v[136:137], v215 offset:10400
	ds_read_b64_tr_b16 v[134:135], v215 offset:9248
	ds_read_b64_tr_b16 v[196:197], v225 offset:36096
	ds_read_b64_tr_b16 v[194:195], v225 offset:33920
	ds_read_b64_tr_b16 v[200:201], v225 offset:36128
	ds_read_b64_tr_b16 v[198:199], v225 offset:33952
	s_waitcnt lgkmcnt(10)
	v_mfma_f32_16x16x32_bf16 v[126:129], v[178:181], v[162:165], v[126:129]
	s_waitcnt lgkmcnt(8)
	v_mfma_f32_16x16x32_bf16 v[122:125], v[178:181], v[142:145], v[122:125]
	v_mfma_f32_16x16x32_bf16 v[118:121], v[182:185], v[162:165], v[118:121]
	v_mfma_f32_16x16x32_bf16 v[114:117], v[182:185], v[142:145], v[114:117]
	ds_read_b64_tr_b16 v[180:181], v225 offset:36160
	ds_read_b64_tr_b16 v[178:179], v225 offset:33984
	ds_read_b64_tr_b16 v[184:185], v225 offset:36192
	ds_read_b64_tr_b16 v[182:183], v225 offset:34016
	v_mfma_f32_16x16x32_bf16 v[110:113], v[186:189], v[162:165], v[110:113]
	v_mfma_f32_16x16x32_bf16 v[106:109], v[186:189], v[142:145], v[106:109]
	v_mfma_f32_16x16x32_bf16 v[102:105], v[190:193], v[162:165], v[102:105]
	v_mfma_f32_16x16x32_bf16 v[98:101], v[190:193], v[142:145], v[98:101]
	ds_read_b64_tr_b16 v[188:189], v225 offset:36224
	ds_read_b64_tr_b16 v[186:187], v225 offset:34048
	ds_read_b64_tr_b16 v[192:193], v225 offset:36256
	ds_read_b64_tr_b16 v[190:191], v225 offset:34080
	s_waitcnt lgkmcnt(10)
	v_mfma_f32_16x16x32_bf16 v[94:97], v[194:197], v[162:165], v[94:97]
	v_mfma_f32_16x16x32_bf16 v[90:93], v[194:197], v[142:145], v[90:93]
	s_waitcnt lgkmcnt(8)
	v_mfma_f32_16x16x32_bf16 v[86:89], v[198:201], v[162:165], v[86:89]
	v_mfma_f32_16x16x32_bf16 v[82:85], v[198:201], v[142:145], v[82:85]
	ds_read_b64_tr_b16 v[196:197], v225 offset:36288
	ds_read_b64_tr_b16 v[194:195], v225 offset:34112
	ds_read_b64_tr_b16 v[200:201], v225 offset:36320
	ds_read_b64_tr_b16 v[198:199], v225 offset:34144
	s_waitcnt lgkmcnt(10)
	v_mfma_f32_16x16x32_bf16 v[78:81], v[178:181], v[162:165], v[78:81]
	v_mfma_f32_16x16x32_bf16 v[74:77], v[178:181], v[142:145], v[74:77]
	s_waitcnt lgkmcnt(8)
	v_mfma_f32_16x16x32_bf16 v[70:73], v[182:185], v[162:165], v[70:73]
	v_mfma_f32_16x16x32_bf16 v[66:69], v[182:185], v[142:145], v[66:69]
	ds_read_b64_tr_b16 v[180:181], v225 offset:36352
	ds_read_b64_tr_b16 v[178:179], v225 offset:34176
	ds_read_b64_tr_b16 v[184:185], v225 offset:36384
	ds_read_b64_tr_b16 v[182:183], v225 offset:34208
	s_waitcnt lgkmcnt(10)
	v_mfma_f32_16x16x32_bf16 v[54:57], v[186:189], v[162:165], v[54:57]
	v_mfma_f32_16x16x32_bf16 v[50:53], v[186:189], v[142:145], v[50:53]
	s_waitcnt lgkmcnt(8)
	v_mfma_f32_16x16x32_bf16 v[46:49], v[190:193], v[162:165], v[46:49]
	v_mfma_f32_16x16x32_bf16 v[42:45], v[190:193], v[142:145], v[42:45]
	ds_read_b64_tr_b16 v[188:189], v225 offset:36416
	ds_read_b64_tr_b16 v[186:187], v225 offset:34240
	ds_read_b64_tr_b16 v[192:193], v225 offset:36448
	ds_read_b64_tr_b16 v[190:191], v225 offset:34272
	s_waitcnt lgkmcnt(10)
	v_mfma_f32_16x16x32_bf16 v[26:29], v[194:197], v[162:165], v[26:29]
	v_mfma_f32_16x16x32_bf16 v[22:25], v[194:197], v[142:145], v[22:25]
	s_waitcnt lgkmcnt(8)
	v_mfma_f32_16x16x32_bf16 v[18:21], v[198:201], v[162:165], v[18:21]
	v_mfma_f32_16x16x32_bf16 v[14:17], v[198:201], v[142:145], v[14:17]
	ds_read_b64_tr_b16 v[196:197], v225 offset:53376
	ds_read_b64_tr_b16 v[194:195], v225 offset:51200
	ds_read_b64_tr_b16 v[200:201], v225 offset:53408
	ds_read_b64_tr_b16 v[198:199], v225 offset:51232
	s_waitcnt lgkmcnt(8)
	v_mfma_f32_16x16x32_bf16 v[62:65], v[182:185], v[162:165], v[62:65]
	v_mfma_f32_16x16x32_bf16 v[58:61], v[182:185], v[142:145], v[58:61]
	v_mfma_f32_16x16x32_bf16 v[202:205], v[178:181], v[162:165], v[10:13]
	v_mfma_f32_16x16x32_bf16 v[178:181], v[178:181], v[142:145], v[6:9]
	s_nop 2
	ds_read_b64_tr_b16 v[8:9], v225 offset:53440
	ds_read_b64_tr_b16 v[6:7], v225 offset:51264
	ds_read_b64_tr_b16 v[12:13], v225 offset:53472
	ds_read_b64_tr_b16 v[10:11], v225 offset:51296
	s_waitcnt lgkmcnt(10)
	v_mfma_f32_16x16x32_bf16 v[182:185], v[186:189], v[162:165], v[38:41]
	v_mfma_f32_16x16x32_bf16 v[186:189], v[186:189], v[142:145], v[34:37]
	s_waitcnt lgkmcnt(8)
	v_mfma_f32_16x16x32_bf16 v[244:247], v[190:193], v[162:165], v[30:33]
	v_mfma_f32_16x16x32_bf16 v[234:237], v[190:193], v[142:145], v[2:5]
	s_nop 2
	ds_read_b64_tr_b16 v[4:5], v225 offset:53504
	ds_read_b64_tr_b16 v[2:3], v225 offset:51328
	ds_read_b64_tr_b16 v[32:33], v225 offset:53536
	ds_read_b64_tr_b16 v[30:31], v225 offset:51360
	s_waitcnt lgkmcnt(10)
	v_mfma_f32_16x16x32_bf16 v[126:129], v[194:197], v[130:133], v[126:129]
	v_mfma_f32_16x16x32_bf16 v[122:125], v[194:197], v[134:137], v[122:125]
	s_waitcnt lgkmcnt(8)
	v_mfma_f32_16x16x32_bf16 v[118:121], v[198:201], v[130:133], v[118:121]
	v_mfma_f32_16x16x32_bf16 v[114:117], v[198:201], v[134:137], v[114:117]
	ds_read_b64_tr_b16 v[36:37], v225 offset:53568
	ds_read_b64_tr_b16 v[34:35], v225 offset:51392
	ds_read_b64_tr_b16 v[40:41], v225 offset:53600
	ds_read_b64_tr_b16 v[38:39], v225 offset:51424
	s_waitcnt lgkmcnt(10)
	v_mfma_f32_16x16x32_bf16 v[110:113], v[6:9], v[130:133], v[110:113]
	v_mfma_f32_16x16x32_bf16 v[106:109], v[6:9], v[134:137], v[106:109]
	s_waitcnt lgkmcnt(8)
	v_mfma_f32_16x16x32_bf16 v[102:105], v[10:13], v[130:133], v[102:105]
	v_mfma_f32_16x16x32_bf16 v[98:101], v[10:13], v[134:137], v[98:101]
	ds_read_b64_tr_b16 v[8:9], v225 offset:53632
	ds_read_b64_tr_b16 v[6:7], v225 offset:51456
	ds_read_b64_tr_b16 v[12:13], v225 offset:53664
	ds_read_b64_tr_b16 v[10:11], v225 offset:51488
	s_waitcnt lgkmcnt(10)
	v_mfma_f32_16x16x32_bf16 v[94:97], v[2:5], v[130:133], v[94:97]
	v_mfma_f32_16x16x32_bf16 v[90:93], v[2:5], v[134:137], v[90:93]
	s_waitcnt lgkmcnt(8)
	v_mfma_f32_16x16x32_bf16 v[86:89], v[30:33], v[130:133], v[86:89]
	v_mfma_f32_16x16x32_bf16 v[82:85], v[30:33], v[134:137], v[82:85]
	ds_read_b64_tr_b16 v[32:33], v225 offset:53696
	ds_read_b64_tr_b16 v[30:31], v225 offset:51520
	ds_read_b64_tr_b16 v[192:193], v225 offset:53728
	ds_read_b64_tr_b16 v[190:191], v225 offset:51552
	s_waitcnt lgkmcnt(10)
	v_mfma_f32_16x16x32_bf16 v[78:81], v[34:37], v[130:133], v[78:81]
	v_mfma_f32_16x16x32_bf16 v[74:77], v[34:37], v[134:137], v[74:77]
	s_waitcnt lgkmcnt(8)
	v_mfma_f32_16x16x32_bf16 v[70:73], v[38:41], v[130:133], v[70:73]
	v_mfma_f32_16x16x32_bf16 v[66:69], v[38:41], v[134:137], v[66:69]
	ds_read_b64_tr_b16 v[40:41], v225 offset:53760
	ds_read_b64_tr_b16 v[38:39], v225 offset:51584
	ds_read_b64_tr_b16 v[196:197], v225 offset:53792
	ds_read_b64_tr_b16 v[194:195], v225 offset:51616
	s_waitcnt lgkmcnt(10)
	v_mfma_f32_16x16x32_bf16 v[54:57], v[6:9], v[130:133], v[54:57]
	v_mfma_f32_16x16x32_bf16 v[50:53], v[6:9], v[134:137], v[50:53]
	s_waitcnt lgkmcnt(8)
	v_mfma_f32_16x16x32_bf16 v[46:49], v[10:13], v[130:133], v[46:49]
	v_mfma_f32_16x16x32_bf16 v[42:45], v[10:13], v[134:137], v[42:45]
	ds_read_b64_tr_b16 v[200:201], v225 offset:53824
	ds_read_b64_tr_b16 v[198:199], v225 offset:51648
	ds_read_b64_tr_b16 v[240:241], v225 offset:53856
	ds_read_b64_tr_b16 v[238:239], v225 offset:51680
	s_waitcnt lgkmcnt(10)
	v_mfma_f32_16x16x32_bf16 v[2:5], v[30:33], v[130:133], v[26:29]
	v_mfma_f32_16x16x32_bf16 v[6:9], v[30:33], v[134:137], v[22:25]
	s_waitcnt lgkmcnt(8)
	v_mfma_f32_16x16x32_bf16 v[10:13], v[190:193], v[130:133], v[18:21]
	v_mfma_f32_16x16x32_bf16 v[14:17], v[190:193], v[134:137], v[14:17]
	s_waitcnt lgkmcnt(6)
	v_mfma_f32_16x16x32_bf16 v[34:37], v[38:41], v[130:133], v[202:205]
	v_mfma_f32_16x16x32_bf16 v[30:33], v[38:41], v[134:137], v[178:181]
	s_waitcnt lgkmcnt(4)
	v_mfma_f32_16x16x32_bf16 v[38:41], v[194:197], v[130:133], v[62:65]
	v_mfma_f32_16x16x32_bf16 v[58:61], v[194:197], v[134:137], v[58:61]
	s_waitcnt lgkmcnt(2)
	v_mfma_f32_16x16x32_bf16 v[178:181], v[198:201], v[130:133], v[182:185]
	v_mfma_f32_16x16x32_bf16 v[182:185], v[198:201], v[134:137], v[186:189]
	s_waitcnt lgkmcnt(0)
	v_mfma_f32_16x16x32_bf16 v[190:193], v[238:241], v[130:133], v[244:247]
	v_mfma_f32_16x16x32_bf16 v[186:189], v[238:241], v[134:137], v[234:237]
	s_waitcnt lgkmcnt(0)
	s_barrier
	v_pk_mul_f32 v[22:23], v[220:221], v[6:7]
	v_pk_mul_f32 v[6:7], v[220:221], v[30:31]
	ds_read_b128 v[28:31], v249
	ds_read_b128 v[194:197], v249 offset:64
	s_waitcnt lgkmcnt(1)
	v_mfma_f32_16x16x32_bf16 v[198:201], v[162:165], v[28:31], v[158:161]
	ds_read_b128 v[234:237], v249 offset:5120
	s_nop 1
	ds_read_b128 v[158:161], v249 offset:2624
	v_mov_b32_e32 v219, v218
	v_mfma_f32_16x16x32_bf16 v[174:177], v[142:145], v[28:31], v[174:177]
	ds_read_b128 v[28:31], v249 offset:2560
	v_pk_mul_f32 v[62:63], v[220:221], v[38:39]
	v_pk_mul_f32 v[38:39], v[220:221], v[178:179]
	s_waitcnt lgkmcnt(0)
	v_mfma_f32_16x16x32_bf16 v[202:205], v[162:165], v[28:31], v[154:157]
	v_lshl_add_u64 v[178:179], v[222:223], 0, s[6:7]
	s_nop 1
	ds_read_b128 v[154:157], v249 offset:5184
	s_mov_b32 s0, 0x39f00000
	v_mfma_f32_16x16x32_bf16 v[238:241], v[162:165], v[234:237], v[150:153]
	v_mul_f32_e64 v64, v218, v40
	v_mul_f32_e64 v65, v219, v41
	v_pk_mul_f32 v[40:41], v[218:219], v[180:181]
	v_add_co_u32_e32 v180, vcc, s0, v178
	v_mfma_f32_16x16x32_bf16 v[166:169], v[142:145], v[234:237], v[166:169]
	ds_read_b128 v[234:237], v249 offset:7680
	ds_read_b128 v[150:153], v249 offset:7744
	s_mov_b32 s1, 0x39f20000
	v_mfma_f32_16x16x32_bf16 v[170:173], v[142:145], v[28:31], v[170:173]
	v_addc_co_u32_e32 v181, vcc, 0, v179, vcc
	v_pk_mul_f32 v[18:19], v[220:221], v[10:11]
	s_waitcnt lgkmcnt(1)
	v_mfma_f32_16x16x32_bf16 v[146:149], v[162:165], v[234:237], v[146:149]
	v_mul_f32_e64 v10, v220, v34
	v_mul_f32_e64 v11, v221, v35
	v_pk_mul_f32 v[34:35], v[220:221], v[182:183]
	v_add_co_u32_e32 v182, vcc, s1, v178
	v_mfma_f32_16x16x32_bf16 v[138:141], v[142:145], v[234:237], v[138:141]
	s_mov_b32 s11, 0x39f40000
	v_addc_co_u32_e32 v183, vcc, 0, v179, vcc
	v_mfma_f32_16x16x32_bf16 v[142:145], v[130:133], v[194:197], v[198:201]
	s_add_u32 s6, s6, 0x80000
	v_pk_mul_f32 v[20:21], v[218:219], v[12:13]
	v_pk_mul_f32 v[12:13], v[218:219], v[36:37]
	v_mfma_f32_16x16x32_bf16 v[162:165], v[134:137], v[194:197], v[174:177]
	v_mul_f32_e64 v36, v218, v184
	v_mul_f32_e64 v37, v219, v185
	v_add_co_u32_e32 v184, vcc, s11, v178
	v_mfma_f32_16x16x32_bf16 v[174:177], v[130:133], v[158:161], v[202:205]
	s_mov_b32 s12, 0x39f60000
	v_addc_co_u32_e32 v185, vcc, 0, v179, vcc
	v_mfma_f32_16x16x32_bf16 v[158:161], v[134:137], v[158:161], v[170:173]
	s_addc_u32 s7, s7, 0
	v_pk_mul_f32 v[126:127], v[220:221], v[126:127]
	v_pk_mul_f32 v[122:123], v[220:221], v[122:123]
	v_mfma_f32_16x16x32_bf16 v[170:173], v[130:133], v[154:157], v[238:241]
	v_mul_f32_e64 v118, v220, v118
	v_mul_f32_e64 v119, v221, v119
	v_pk_mul_f32 v[114:115], v[220:221], v[114:115]
	v_pk_mul_f32 v[110:111], v[220:221], v[110:111]
	v_mfma_f32_16x16x32_bf16 v[154:157], v[134:137], v[154:157], v[166:169]
	v_mul_f32_e64 v106, v220, v106
	v_mul_f32_e64 v107, v221, v107
	v_pk_mul_f32 v[102:103], v[220:221], v[102:103]
	v_pk_mul_f32 v[98:99], v[220:221], v[98:99]
	s_waitcnt lgkmcnt(0)
	v_mfma_f32_16x16x32_bf16 v[130:133], v[130:133], v[150:153], v[146:149]
	v_mul_f32_e64 v94, v220, v94
	v_mul_f32_e64 v95, v221, v95
	v_pk_mul_f32 v[90:91], v[220:221], v[90:91]
	v_pk_mul_f32 v[86:87], v[220:221], v[86:87]
	v_mfma_f32_16x16x32_bf16 v[134:137], v[134:137], v[150:153], v[138:141]
	v_mul_f32_e64 v82, v220, v82
	v_mul_f32_e64 v83, v221, v83
	v_pk_mul_f32 v[78:79], v[220:221], v[78:79]
	v_pk_mul_f32 v[74:75], v[220:221], v[74:75]
	v_pk_mul_f32 v[70:71], v[220:221], v[70:71]
	v_pk_mul_f32 v[66:67], v[220:221], v[66:67]
	v_pk_mul_f32 v[54:55], v[220:221], v[54:55]
	v_pk_mul_f32 v[128:129], v[218:219], v[128:129]
	v_pk_mul_f32 v[50:51], v[220:221], v[50:51]
	v_pk_mul_f32 v[124:125], v[218:219], v[124:125]
	v_pk_mul_f32 v[46:47], v[220:221], v[46:47]
	v_pk_mul_f32 v[120:121], v[218:219], v[120:121]
	v_pk_mul_f32 v[42:43], v[220:221], v[42:43]
	v_pk_mul_f32 v[116:117], v[218:219], v[116:117]
	v_pk_mul_f32 v[26:27], v[220:221], v[2:3]
	v_pk_mul_f32 v[112:113], v[218:219], v[112:113]
	v_pk_mul_f32 v[108:109], v[218:219], v[108:109]
	v_pk_mul_f32 v[104:105], v[218:219], v[104:105]
	v_pk_mul_f32 v[14:15], v[220:221], v[14:15]
	v_pk_mul_f32 v[100:101], v[218:219], v[100:101]
	v_pk_mul_f32 v[96:97], v[218:219], v[96:97]
	v_pk_mul_f32 v[92:93], v[218:219], v[92:93]
	v_pk_mul_f32 v[88:89], v[218:219], v[88:89]
	v_pk_mul_f32 v[84:85], v[218:219], v[84:85]
	v_pk_mul_f32 v[80:81], v[218:219], v[80:81]
	v_pk_mul_f32 v[58:59], v[220:221], v[58:59]
	v_pk_mul_f32 v[76:77], v[218:219], v[76:77]
	v_pk_mul_f32 v[72:73], v[218:219], v[72:73]
	v_pk_mul_f32 v[68:69], v[218:219], v[68:69]
	v_pk_mul_f32 v[56:57], v[218:219], v[56:57]
	v_pk_mul_f32 v[52:53], v[218:219], v[52:53]
	v_pk_mul_f32 v[30:31], v[220:221], v[190:191]
	v_pk_mul_f32 v[48:49], v[218:219], v[48:49]
	v_pk_mul_f32 v[2:3], v[220:221], v[186:187]
	v_pk_mul_f32 v[44:45], v[218:219], v[44:45]
	v_pk_mul_f32 v[28:29], v[218:219], v[4:5]
	v_pk_mul_f32 v[24:25], v[218:219], v[8:9]
	v_pk_mul_f32 v[16:17], v[218:219], v[16:17]
	v_pk_mul_f32 v[8:9], v[218:219], v[32:33]
	v_pk_mul_f32 v[60:61], v[218:219], v[60:61]
	v_pk_mul_f32 v[32:33], v[218:219], v[192:193]
	v_pk_mul_f32 v[4:5], v[218:219], v[188:189]
	v_add_co_u32_e32 v166, vcc, s12, v178
	s_cmp_eq_u32 s6, 0x1000000
	v_cvt_pk_bf16_f32 v138, v142, v143
	v_cvt_pk_bf16_f32 v139, v144, v145
	v_addc_co_u32_e32 v167, vcc, 0, v179, vcc
	v_cvt_pk_bf16_f32 v140, v162, v163
	v_cvt_pk_bf16_f32 v141, v164, v165
	v_cvt_pk_bf16_f32 v142, v174, v175
	v_cvt_pk_bf16_f32 v143, v176, v177
	v_cvt_pk_bf16_f32 v144, v158, v159
	v_cvt_pk_bf16_f32 v145, v160, v161
	v_cvt_pk_bf16_f32 v146, v170, v171
	v_cvt_pk_bf16_f32 v147, v172, v173
	v_cvt_pk_bf16_f32 v148, v154, v155
	v_cvt_pk_bf16_f32 v149, v156, v157
	v_cvt_pk_bf16_f32 v130, v130, v131
	v_cvt_pk_bf16_f32 v131, v132, v133
	v_cvt_pk_bf16_f32 v132, v134, v135
	v_cvt_pk_bf16_f32 v133, v136, v137
	global_store_dwordx2 v[180:181], v[138:139], off
	global_store_dwordx2 v[180:181], v[140:141], off offset:32
	global_store_dwordx2 v[182:183], v[142:143], off
	global_store_dwordx2 v[182:183], v[144:145], off offset:32
	global_store_dwordx2 v[184:185], v[146:147], off
	global_store_dwordx2 v[184:185], v[148:149], off offset:32
	global_store_dwordx2 v[166:167], v[130:131], off
	global_store_dwordx2 v[166:167], v[132:133], off offset:32
	s_cbranch_scc0 .LBB0_415
	s_waitcnt lgkmcnt(0)
	s_barrier
	s_branch .LBB0_411

.LBB0_1910:
	s_ashr_i32 s9, s8, 31
	s_lshl_b64 s[0:1], s[8:9], 12
	s_lshl_b32 s10, s12, 5
	s_and_b32 s9, s87, 0xc00
	s_ashr_i32 s11, s10, 31
	s_or_b32 s0, s0, s9
	s_andn2_b32 s15, s15, 63
	s_or_b64 s[0:1], s[0:1], s[66:67]
	s_lshl_b64 s[10:11], s[10:11], 1
	s_add_u32 s0, s0, s10
	v_or_b32_e32 v1, s15, v193
	s_addc_u32 s1, s1, s11
	v_mov_b32_e32 v122, 0
	v_lshl_add_u64 v[190:191], v[184:185], 0, s[0:1]
	s_mov_b64 s[10:11], 0
	v_add_u32_e32 v1, v195, v1
	v_mov_b32_e32 v123, v122
	v_mov_b32_e32 v124, v122
	v_mov_b32_e32 v125, v122
	v_mov_b32_e32 v126, v122
	v_mov_b32_e32 v127, v122
	v_mov_b32_e32 v128, v122
	v_mov_b32_e32 v129, v122
	v_mov_b32_e32 v114, v122
	v_mov_b32_e32 v115, v122
	v_mov_b32_e32 v116, v122
	v_mov_b32_e32 v117, v122
	v_mov_b32_e32 v118, v122
	v_mov_b32_e32 v119, v122
	v_mov_b32_e32 v120, v122
	v_mov_b32_e32 v121, v122
	v_mov_b32_e32 v106, v122
	v_mov_b32_e32 v107, v122
	v_mov_b32_e32 v108, v122
	v_mov_b32_e32 v109, v122
	v_mov_b32_e32 v110, v122
	v_mov_b32_e32 v111, v122
	v_mov_b32_e32 v112, v122
	v_mov_b32_e32 v113, v122
	v_mov_b32_e32 v98, v122
	v_mov_b32_e32 v99, v122
	v_mov_b32_e32 v100, v122
	v_mov_b32_e32 v101, v122
	v_mov_b32_e32 v102, v122
	v_mov_b32_e32 v103, v122
	v_mov_b32_e32 v104, v122
	v_mov_b32_e32 v105, v122
	v_mov_b32_e32 v90, v122
	v_mov_b32_e32 v91, v122
	v_mov_b32_e32 v92, v122
	v_mov_b32_e32 v93, v122
	v_mov_b32_e32 v94, v122
	v_mov_b32_e32 v95, v122
	v_mov_b32_e32 v96, v122
	v_mov_b32_e32 v97, v122
	v_mov_b32_e32 v82, v122
	v_mov_b32_e32 v83, v122
	v_mov_b32_e32 v84, v122
	v_mov_b32_e32 v85, v122
	v_mov_b32_e32 v86, v122
	v_mov_b32_e32 v87, v122
	v_mov_b32_e32 v88, v122
	v_mov_b32_e32 v89, v122
	v_mov_b32_e32 v74, v122
	v_mov_b32_e32 v75, v122
	v_mov_b32_e32 v76, v122
	v_mov_b32_e32 v77, v122
	v_mov_b32_e32 v78, v122
	v_mov_b32_e32 v79, v122
	v_mov_b32_e32 v80, v122
	v_mov_b32_e32 v81, v122
	v_mov_b32_e32 v66, v122
	v_mov_b32_e32 v67, v122
	v_mov_b32_e32 v68, v122
	v_mov_b32_e32 v69, v122
	v_mov_b32_e32 v70, v122
	v_mov_b32_e32 v71, v122
	v_mov_b32_e32 v72, v122
	v_mov_b32_e32 v73, v122
	v_mov_b32_e32 v58, v122
	v_mov_b32_e32 v59, v122
	v_mov_b32_e32 v60, v122
	v_mov_b32_e32 v61, v122
	v_mov_b32_e32 v62, v122
	v_mov_b32_e32 v63, v122
	v_mov_b32_e32 v64, v122
	v_mov_b32_e32 v65, v122
	v_mov_b32_e32 v50, v122
	v_mov_b32_e32 v51, v122
	v_mov_b32_e32 v52, v122
	v_mov_b32_e32 v53, v122
	v_mov_b32_e32 v54, v122
	v_mov_b32_e32 v55, v122
	v_mov_b32_e32 v56, v122
	v_mov_b32_e32 v57, v122
	v_mov_b32_e32 v42, v122
	v_mov_b32_e32 v43, v122
	v_mov_b32_e32 v44, v122
	v_mov_b32_e32 v45, v122
	v_mov_b32_e32 v46, v122
	v_mov_b32_e32 v47, v122
	v_mov_b32_e32 v48, v122
	v_mov_b32_e32 v49, v122
	v_mov_b32_e32 v34, v122
	v_mov_b32_e32 v35, v122
	v_mov_b32_e32 v36, v122
	v_mov_b32_e32 v37, v122
	v_mov_b32_e32 v38, v122
	v_mov_b32_e32 v39, v122
	v_mov_b32_e32 v40, v122
	v_mov_b32_e32 v41, v122
	v_mov_b32_e32 v26, v122
	v_mov_b32_e32 v27, v122
	v_mov_b32_e32 v28, v122
	v_mov_b32_e32 v29, v122
	v_mov_b32_e32 v30, v122
	v_mov_b32_e32 v31, v122
	v_mov_b32_e32 v32, v122
	v_mov_b32_e32 v33, v122
	v_mov_b32_e32 v18, v122
	v_mov_b32_e32 v19, v122
	v_mov_b32_e32 v20, v122
	v_mov_b32_e32 v21, v122
	v_mov_b32_e32 v22, v122
	v_mov_b32_e32 v23, v122
	v_mov_b32_e32 v24, v122
	v_mov_b32_e32 v25, v122
	v_mov_b32_e32 v10, v122
	v_mov_b32_e32 v11, v122
	v_mov_b32_e32 v12, v122
	v_mov_b32_e32 v13, v122
	v_mov_b32_e32 v14, v122
	v_mov_b32_e32 v15, v122
	v_mov_b32_e32 v16, v122
	v_mov_b32_e32 v17, v122
	v_mov_b32_e32 v2, v122
	v_mov_b32_e32 v3, v122
	v_mov_b32_e32 v4, v122
	v_mov_b32_e32 v5, v122
	v_mov_b32_e32 v6, v122
	v_mov_b32_e32 v7, v122
	v_mov_b32_e32 v8, v122
	v_mov_b32_e32 v9, v122
	v_lshrrev_b32_e32 v196, 2, v0
	v_and_b32_e32 v198, 3, v0
	v_lshlrev_b32_e32 v197, 12, v196
	v_lshlrev_b32_e32 v196, 11, v196
	v_lshl_or_b32 v197, v198, 7, v197
	v_lshl_or_b32 v196, v198, 7, v196
.LBB0_1911:
	s_waitcnt lgkmcnt(0)
	s_barrier
	s_lshl_b32 s98, s13, 22
	s_lshl_b32 s99, s14, 9
	s_add_i32 s98, s98, s99
	s_lshr_b32 s99, s10, 1
	s_add_i32 s98, s98, s99
	s_add_i32 s98, s98, 0x21f40000
	s_add_u32 s100, s48, s98
	s_addc_u32 s101, s49, 0
	s_nop 0
	global_load_dword v198, v196, s[100:101]
	s_add_u32 s100, s100, 0x2000000
	s_addc_u32 s101, s101, 0
	s_nop 0
	global_load_dword v198, v196, s[100:101]
	s_lshl_b32 s98, s13, 23
	s_lshl_b32 s99, s14, 10
	s_add_i32 s98, s98, s99
	s_add_i32 s98, s98, s66
	s_add_i32 s98, s98, s10
	s_add_i32 s98, s98, 0x25f80000
	s_add_u32 s100, s48, s98
	s_addc_u32 s101, s49, 0
	s_nop 0
	global_load_dword v198, v197, s[100:101]
	ds_read2_b64 v[130:133], v217 offset1:4
	ds_read2_b64 v[134:137], v221 offset0:32 offset1:36
	ds_read2_b64 v[138:141], v222 offset0:64 offset1:68
	ds_read2_b64 v[142:145], v223 offset0:96 offset1:100
	ds_read2_b64 v[146:149], v217 offset0:8 offset1:12
	ds_read2_b64 v[150:153], v221 offset0:40 offset1:44
	ds_read2_b64 v[154:157], v222 offset0:72 offset1:76
	ds_read2_b64 v[158:161], v223 offset0:104 offset1:108
	v_cvt_pk_bf16_f32 v162, v6, v7
	v_cvt_pk_bf16_f32 v163, v8, v9
	v_cvt_pk_bf16_f32 v164, v14, v15
	v_cvt_pk_bf16_f32 v165, v16, v17
	v_cvt_pk_bf16_f32 v228, v2, v3
	v_cvt_pk_bf16_f32 v229, v4, v5
	v_cvt_pk_bf16_f32 v230, v10, v11
	v_cvt_pk_bf16_f32 v231, v12, v13
	s_waitcnt lgkmcnt(0)
	v_mfma_f32_16x16x32_bf16 v[166:169], v[162:165], v[130:133], 0
	v_mfma_f32_16x16x32_bf16 v[170:173], v[162:165], v[134:137], 0
	v_mfma_f32_16x16x32_bf16 v[174:177], v[162:165], v[138:141], 0
	v_mfma_f32_16x16x32_bf16 v[162:165], v[162:165], v[142:145], 0
	v_mfma_f32_16x16x32_bf16 v[130:133], v[228:231], v[130:133], 0
	v_mfma_f32_16x16x32_bf16 v[134:137], v[228:231], v[134:137], 0
	v_mfma_f32_16x16x32_bf16 v[138:141], v[228:231], v[138:141], 0
	v_mfma_f32_16x16x32_bf16 v[142:145], v[228:231], v[142:145], 0
	ds_read2_b64 v[228:231], v217 offset0:16 offset1:20
	ds_read2_b64 v[232:235], v221 offset0:48 offset1:52
	ds_read2_b64 v[236:239], v222 offset0:80 offset1:84
	ds_read2_b64 v[240:243], v223 offset0:112 offset1:116
	v_cvt_pk_bf16_f32 v244, v22, v23
	v_cvt_pk_bf16_f32 v245, v24, v25
	v_cvt_pk_bf16_f32 v246, v30, v31
	v_cvt_pk_bf16_f32 v247, v32, v33
	s_nop 1
	v_mfma_f32_16x16x32_bf16 v[166:169], v[244:247], v[146:149], v[166:169]
	v_mfma_f32_16x16x32_bf16 v[170:173], v[244:247], v[150:153], v[170:173]
	v_mfma_f32_16x16x32_bf16 v[174:177], v[244:247], v[154:157], v[174:177]
	v_mfma_f32_16x16x32_bf16 v[162:165], v[244:247], v[158:161], v[162:165]
	v_cvt_pk_bf16_f32 v244, v18, v19
	v_cvt_pk_bf16_f32 v245, v20, v21
	v_cvt_pk_bf16_f32 v246, v26, v27
	v_cvt_pk_bf16_f32 v247, v28, v29
	s_nop 1
	v_mfma_f32_16x16x32_bf16 v[130:133], v[244:247], v[146:149], v[130:133]
	v_mfma_f32_16x16x32_bf16 v[134:137], v[244:247], v[150:153], v[134:137]
	v_mfma_f32_16x16x32_bf16 v[138:141], v[244:247], v[154:157], v[138:141]
	v_mfma_f32_16x16x32_bf16 v[142:145], v[244:247], v[158:161], v[142:145]
	ds_read2_b64 v[146:149], v217 offset0:24 offset1:28
	ds_read2_b64 v[150:153], v221 offset0:56 offset1:60
	ds_read2_b64 v[154:157], v222 offset0:88 offset1:92
	ds_read2_b64 v[158:161], v223 offset0:120 offset1:124
	v_cvt_pk_bf16_f32 v244, v38, v39
	v_cvt_pk_bf16_f32 v245, v40, v41
	v_cvt_pk_bf16_f32 v246, v46, v47
	v_cvt_pk_bf16_f32 v247, v48, v49
	s_waitcnt lgkmcnt(0)
	s_nop 0
	v_mfma_f32_16x16x32_bf16 v[166:169], v[244:247], v[228:231], v[166:169]
	v_mfma_f32_16x16x32_bf16 v[170:173], v[244:247], v[232:235], v[170:173]
	v_mfma_f32_16x16x32_bf16 v[174:177], v[244:247], v[236:239], v[174:177]
	v_mfma_f32_16x16x32_bf16 v[162:165], v[244:247], v[240:243], v[162:165]
	v_cvt_pk_bf16_f32 v244, v34, v35
	v_cvt_pk_bf16_f32 v245, v36, v37
	v_cvt_pk_bf16_f32 v246, v42, v43
	v_cvt_pk_bf16_f32 v247, v44, v45
	s_nop 1
	v_mfma_f32_16x16x32_bf16 v[130:133], v[244:247], v[228:231], v[130:133]
	v_mfma_f32_16x16x32_bf16 v[134:137], v[244:247], v[232:235], v[134:137]
	v_mfma_f32_16x16x32_bf16 v[138:141], v[244:247], v[236:239], v[138:141]
	v_mfma_f32_16x16x32_bf16 v[142:145], v[244:247], v[240:243], v[142:145]
	ds_read2_b64 v[228:231], v217 offset0:32 offset1:36
	ds_read2_b64 v[232:235], v221 offset0:64 offset1:68
	ds_read2_b64 v[236:239], v222 offset0:96 offset1:100
	ds_read2_b64 v[240:243], v223 offset0:128 offset1:132
	v_cvt_pk_bf16_f32 v244, v54, v55
	v_cvt_pk_bf16_f32 v245, v56, v57
	v_cvt_pk_bf16_f32 v246, v62, v63
	v_cvt_pk_bf16_f32 v247, v64, v65
	s_nop 1
	v_mfma_f32_16x16x32_bf16 v[166:169], v[244:247], v[146:149], v[166:169]
	v_mfma_f32_16x16x32_bf16 v[170:173], v[244:247], v[150:153], v[170:173]
	v_mfma_f32_16x16x32_bf16 v[174:177], v[244:247], v[154:157], v[174:177]
	v_mfma_f32_16x16x32_bf16 v[162:165], v[244:247], v[158:161], v[162:165]
	v_cvt_pk_bf16_f32 v244, v50, v51
	v_cvt_pk_bf16_f32 v245, v52, v53
	v_cvt_pk_bf16_f32 v246, v58, v59
	v_cvt_pk_bf16_f32 v247, v60, v61
	s_nop 1
	v_mfma_f32_16x16x32_bf16 v[130:133], v[244:247], v[146:149], v[130:133]
	v_mfma_f32_16x16x32_bf16 v[134:137], v[244:247], v[150:153], v[134:137]
	v_mfma_f32_16x16x32_bf16 v[138:141], v[244:247], v[154:157], v[138:141]
	v_mfma_f32_16x16x32_bf16 v[142:145], v[244:247], v[158:161], v[142:145]
	ds_read2_b64 v[146:149], v217 offset0:40 offset1:44
	ds_read2_b64 v[150:153], v221 offset0:72 offset1:76
	ds_read2_b64 v[154:157], v222 offset0:104 offset1:108
	ds_read2_b64 v[158:161], v223 offset0:136 offset1:140
	v_cvt_pk_bf16_f32 v244, v70, v71
	v_cvt_pk_bf16_f32 v245, v72, v73
	v_cvt_pk_bf16_f32 v246, v78, v79
	v_cvt_pk_bf16_f32 v247, v80, v81
	s_waitcnt lgkmcnt(0)
	s_nop 0
	v_mfma_f32_16x16x32_bf16 v[166:169], v[244:247], v[228:231], v[166:169]
	v_mfma_f32_16x16x32_bf16 v[170:173], v[244:247], v[232:235], v[170:173]
	v_mfma_f32_16x16x32_bf16 v[174:177], v[244:247], v[236:239], v[174:177]
	v_mfma_f32_16x16x32_bf16 v[162:165], v[244:247], v[240:243], v[162:165]
	v_cvt_pk_bf16_f32 v244, v66, v67
	v_cvt_pk_bf16_f32 v245, v68, v69
	v_cvt_pk_bf16_f32 v246, v74, v75
	v_cvt_pk_bf16_f32 v247, v76, v77
	s_nop 1
	v_mfma_f32_16x16x32_bf16 v[130:133], v[244:247], v[228:231], v[130:133]
	v_mfma_f32_16x16x32_bf16 v[134:137], v[244:247], v[232:235], v[134:137]
	v_mfma_f32_16x16x32_bf16 v[138:141], v[244:247], v[236:239], v[138:141]
	v_mfma_f32_16x16x32_bf16 v[142:145], v[244:247], v[240:243], v[142:145]
	ds_read2_b64 v[228:231], v217 offset0:48 offset1:52
	ds_read2_b64 v[232:235], v221 offset0:80 offset1:84
	ds_read2_b64 v[236:239], v222 offset0:112 offset1:116
	ds_read2_b64 v[240:243], v223 offset0:144 offset1:148
	v_cvt_pk_bf16_f32 v244, v86, v87
	v_cvt_pk_bf16_f32 v245, v88, v89
	v_cvt_pk_bf16_f32 v246, v94, v95
	v_cvt_pk_bf16_f32 v247, v96, v97
	s_nop 1
	v_mfma_f32_16x16x32_bf16 v[166:169], v[244:247], v[146:149], v[166:169]
	v_mfma_f32_16x16x32_bf16 v[170:173], v[244:247], v[150:153], v[170:173]
	v_mfma_f32_16x16x32_bf16 v[174:177], v[244:247], v[154:157], v[174:177]
	v_mfma_f32_16x16x32_bf16 v[162:165], v[244:247], v[158:161], v[162:165]
	v_cvt_pk_bf16_f32 v244, v82, v83
	v_cvt_pk_bf16_f32 v245, v84, v85
	v_cvt_pk_bf16_f32 v246, v90, v91
	v_cvt_pk_bf16_f32 v247, v92, v93
	s_nop 1
	v_mfma_f32_16x16x32_bf16 v[130:133], v[244:247], v[146:149], v[130:133]
	v_mfma_f32_16x16x32_bf16 v[134:137], v[244:247], v[150:153], v[134:137]
	v_mfma_f32_16x16x32_bf16 v[138:141], v[244:247], v[154:157], v[138:141]
	v_mfma_f32_16x16x32_bf16 v[142:145], v[244:247], v[158:161], v[142:145]
	ds_read2_b64 v[146:149], v217 offset0:56 offset1:60
	ds_read2_b64 v[150:153], v221 offset0:88 offset1:92
	ds_read2_b64 v[244:247], v222 offset0:120 offset1:124
	ds_read2_b64 v[248:251], v223 offset0:152 offset1:156
	v_cvt_pk_bf16_f32 v154, v102, v103
	v_cvt_pk_bf16_f32 v155, v104, v105
	v_cvt_pk_bf16_f32 v156, v110, v111
	v_cvt_pk_bf16_f32 v157, v112, v113
	s_waitcnt lgkmcnt(0)
	s_nop 0
	v_mfma_f32_16x16x32_bf16 v[158:161], v[154:157], v[228:231], v[166:169]
	v_mfma_f32_16x16x32_bf16 v[166:169], v[154:157], v[232:235], v[170:173]
	v_mfma_f32_16x16x32_bf16 v[170:173], v[154:157], v[236:239], v[174:177]
	v_mfma_f32_16x16x32_bf16 v[154:157], v[154:157], v[240:243], v[162:165]
	s_nop 2
	v_cvt_pk_bf16_f32 v162, v98, v99
	v_cvt_pk_bf16_f32 v163, v100, v101
	v_cvt_pk_bf16_f32 v164, v106, v107
	v_cvt_pk_bf16_f32 v165, v108, v109
	s_nop 1
	v_mfma_f32_16x16x32_bf16 v[174:177], v[162:165], v[228:231], v[130:133]
	v_mfma_f32_16x16x32_bf16 v[228:231], v[162:165], v[232:235], v[134:137]
	v_mfma_f32_16x16x32_bf16 v[232:235], v[162:165], v[236:239], v[138:141]
	v_mfma_f32_16x16x32_bf16 v[162:165], v[162:165], v[240:243], v[142:145]
	s_waitcnt vmcnt(3)
	ds_read_b64_tr_b16 v[236:237], v194 offset:33792
	ds_read_b64_tr_b16 v[240:241], v194 offset:33824
	ds_read_b64_tr_b16 v[204:205], v194 offset:33856
	ds_read_b64_tr_b16 v[208:209], v194 offset:33888
	ds_read_b64_tr_b16 v[238:239], v194 offset:35968
	ds_read_b64_tr_b16 v[242:243], v194 offset:36000
	ds_read_b64_tr_b16 v[206:207], v194 offset:36032
	ds_read_b64_tr_b16 v[210:211], v194 offset:36064
	v_cvt_pk_bf16_f32 v142, v118, v119
	v_cvt_pk_bf16_f32 v143, v120, v121
	v_cvt_pk_bf16_f32 v144, v126, v127
	v_cvt_pk_bf16_f32 v145, v128, v129
	s_nop 1
	v_mfma_f32_16x16x32_bf16 v[134:137], v[142:145], v[150:153], v[166:169]
	s_nop 2
	v_cvt_pk_bf16_f32 v166, v114, v115
	v_cvt_pk_bf16_f32 v167, v116, v117
	v_cvt_pk_bf16_f32 v168, v122, v123
	v_cvt_pk_bf16_f32 v169, v124, v125
	v_mfma_f32_16x16x32_bf16 v[130:133], v[142:145], v[146:149], v[158:161]
	v_mfma_f32_16x16x32_bf16 v[138:141], v[142:145], v[244:247], v[170:173]
	v_mfma_f32_16x16x32_bf16 v[142:145], v[142:145], v[248:251], v[154:157]
	v_mfma_f32_16x16x32_bf16 v[158:161], v[166:169], v[146:149], v[174:177]
	v_mfma_f32_16x16x32_bf16 v[154:157], v[166:169], v[150:153], v[228:231]
	v_mfma_f32_16x16x32_bf16 v[150:153], v[166:169], v[244:247], v[232:235]
	v_mfma_f32_16x16x32_bf16 v[146:149], v[166:169], v[248:251], v[162:165]
	s_nop 2
	ds_read_b64_tr_b16 v[164:165], v1 offset:1152
	ds_read_b64_tr_b16 v[162:163], v1
	ds_read_b64_tr_b16 v[172:173], v1 offset:1184
	ds_read_b64_tr_b16 v[170:171], v1 offset:32
	ds_read_b64_tr_b16 v[166:167], v1 offset:9216
	ds_read_b64_tr_b16 v[168:169], v1 offset:10368
	ds_read_b64_tr_b16 v[176:177], v1 offset:10400
	ds_read_b64_tr_b16 v[174:175], v1 offset:9248
	ds_read_b64_tr_b16 v[230:231], v194 offset:36096
	ds_read_b64_tr_b16 v[228:229], v194 offset:33920
	ds_read_b64_tr_b16 v[234:235], v194 offset:36128
	ds_read_b64_tr_b16 v[232:233], v194 offset:33952
	s_waitcnt lgkmcnt(10)
	v_mfma_f32_16x16x32_bf16 v[6:9], v[236:239], v[162:165], v[6:9]
	s_waitcnt lgkmcnt(8)
	v_mfma_f32_16x16x32_bf16 v[2:5], v[236:239], v[170:173], v[2:5]
	v_mfma_f32_16x16x32_bf16 v[14:17], v[240:243], v[162:165], v[14:17]
	v_mfma_f32_16x16x32_bf16 v[10:13], v[240:243], v[170:173], v[10:13]
	ds_read_b64_tr_b16 v[238:239], v194 offset:36160
	ds_read_b64_tr_b16 v[236:237], v194 offset:33984
	ds_read_b64_tr_b16 v[242:243], v194 offset:36192
	ds_read_b64_tr_b16 v[240:241], v194 offset:34016
	v_mfma_f32_16x16x32_bf16 v[22:25], v[204:207], v[162:165], v[22:25]
	v_mfma_f32_16x16x32_bf16 v[18:21], v[204:207], v[170:173], v[18:21]
	v_mfma_f32_16x16x32_bf16 v[30:33], v[208:211], v[162:165], v[30:33]
	v_mfma_f32_16x16x32_bf16 v[26:29], v[208:211], v[170:173], v[26:29]
	ds_read_b64_tr_b16 v[206:207], v194 offset:36224
	ds_read_b64_tr_b16 v[204:205], v194 offset:34048
	ds_read_b64_tr_b16 v[210:211], v194 offset:36256
	ds_read_b64_tr_b16 v[208:209], v194 offset:34080
	s_waitcnt lgkmcnt(10)
	v_mfma_f32_16x16x32_bf16 v[38:41], v[228:231], v[162:165], v[38:41]
	v_mfma_f32_16x16x32_bf16 v[34:37], v[228:231], v[170:173], v[34:37]
	s_waitcnt lgkmcnt(8)
	v_mfma_f32_16x16x32_bf16 v[46:49], v[232:235], v[162:165], v[46:49]
	v_mfma_f32_16x16x32_bf16 v[42:45], v[232:235], v[170:173], v[42:45]
	ds_read_b64_tr_b16 v[230:231], v194 offset:36288
	ds_read_b64_tr_b16 v[228:229], v194 offset:34112
	ds_read_b64_tr_b16 v[234:235], v194 offset:36320
	ds_read_b64_tr_b16 v[232:233], v194 offset:34144
	s_waitcnt lgkmcnt(10)
	v_mfma_f32_16x16x32_bf16 v[54:57], v[236:239], v[162:165], v[54:57]
	v_mfma_f32_16x16x32_bf16 v[50:53], v[236:239], v[170:173], v[50:53]
	s_waitcnt lgkmcnt(8)
	v_mfma_f32_16x16x32_bf16 v[62:65], v[240:243], v[162:165], v[62:65]
	v_mfma_f32_16x16x32_bf16 v[58:61], v[240:243], v[170:173], v[58:61]
	ds_read_b64_tr_b16 v[238:239], v194 offset:36352
	ds_read_b64_tr_b16 v[236:237], v194 offset:34176
	ds_read_b64_tr_b16 v[242:243], v194 offset:36384
	ds_read_b64_tr_b16 v[240:241], v194 offset:34208
	s_waitcnt lgkmcnt(10)
	v_mfma_f32_16x16x32_bf16 v[70:73], v[204:207], v[162:165], v[70:73]
	v_mfma_f32_16x16x32_bf16 v[66:69], v[204:207], v[170:173], v[66:69]
	s_waitcnt lgkmcnt(8)
	v_mfma_f32_16x16x32_bf16 v[78:81], v[208:211], v[162:165], v[78:81]
	v_mfma_f32_16x16x32_bf16 v[74:77], v[208:211], v[170:173], v[74:77]
	ds_read_b64_tr_b16 v[206:207], v194 offset:36416
	ds_read_b64_tr_b16 v[204:205], v194 offset:34240
	ds_read_b64_tr_b16 v[210:211], v194 offset:36448
	ds_read_b64_tr_b16 v[208:209], v194 offset:34272
	s_waitcnt lgkmcnt(10)
	v_mfma_f32_16x16x32_bf16 v[86:89], v[228:231], v[162:165], v[86:89]
	v_mfma_f32_16x16x32_bf16 v[82:85], v[228:231], v[170:173], v[82:85]
	s_waitcnt lgkmcnt(8)
	v_mfma_f32_16x16x32_bf16 v[94:97], v[232:235], v[162:165], v[94:97]
	v_mfma_f32_16x16x32_bf16 v[90:93], v[232:235], v[170:173], v[90:93]
	ds_read_b64_tr_b16 v[230:231], v194 offset:53376
	ds_read_b64_tr_b16 v[228:229], v194 offset:51200
	ds_read_b64_tr_b16 v[234:235], v194 offset:53408
	ds_read_b64_tr_b16 v[232:233], v194 offset:51232
	s_waitcnt lgkmcnt(10)
	v_mfma_f32_16x16x32_bf16 v[102:105], v[236:239], v[162:165], v[102:105]
	v_mfma_f32_16x16x32_bf16 v[98:101], v[236:239], v[170:173], v[98:101]
	s_waitcnt lgkmcnt(8)
	v_mfma_f32_16x16x32_bf16 v[110:113], v[240:243], v[162:165], v[110:113]
	v_mfma_f32_16x16x32_bf16 v[106:109], v[240:243], v[170:173], v[106:109]
	ds_read_b64_tr_b16 v[238:239], v194 offset:53440
	ds_read_b64_tr_b16 v[236:237], v194 offset:51264
	ds_read_b64_tr_b16 v[242:243], v194 offset:53472
	ds_read_b64_tr_b16 v[240:241], v194 offset:51296
	s_waitcnt lgkmcnt(10)
	v_mfma_f32_16x16x32_bf16 v[118:121], v[204:207], v[162:165], v[118:121]
	v_mfma_f32_16x16x32_bf16 v[114:117], v[204:207], v[170:173], v[114:117]
	s_waitcnt lgkmcnt(8)
	v_mfma_f32_16x16x32_bf16 v[126:129], v[208:211], v[162:165], v[126:129]
	v_mfma_f32_16x16x32_bf16 v[122:125], v[208:211], v[170:173], v[122:125]
	ds_read_b64_tr_b16 v[206:207], v194 offset:53504
	ds_read_b64_tr_b16 v[204:205], v194 offset:51328
	ds_read_b64_tr_b16 v[210:211], v194 offset:53536
	ds_read_b64_tr_b16 v[208:209], v194 offset:51360
	s_waitcnt lgkmcnt(10)
	v_mfma_f32_16x16x32_bf16 v[6:9], v[228:231], v[166:169], v[6:9]
	v_mfma_f32_16x16x32_bf16 v[2:5], v[228:231], v[174:177], v[2:5]
	s_waitcnt lgkmcnt(8)
	v_mfma_f32_16x16x32_bf16 v[14:17], v[232:235], v[166:169], v[14:17]
	v_mfma_f32_16x16x32_bf16 v[10:13], v[232:235], v[174:177], v[10:13]
	ds_read_b64_tr_b16 v[230:231], v194 offset:53568
	ds_read_b64_tr_b16 v[228:229], v194 offset:51392
	ds_read_b64_tr_b16 v[234:235], v194 offset:53600
	ds_read_b64_tr_b16 v[232:233], v194 offset:51424
	s_waitcnt lgkmcnt(10)
	v_mfma_f32_16x16x32_bf16 v[22:25], v[236:239], v[166:169], v[22:25]
	v_mfma_f32_16x16x32_bf16 v[18:21], v[236:239], v[174:177], v[18:21]
	s_waitcnt lgkmcnt(8)
	v_mfma_f32_16x16x32_bf16 v[30:33], v[240:243], v[166:169], v[30:33]
	v_mfma_f32_16x16x32_bf16 v[26:29], v[240:243], v[174:177], v[26:29]
	ds_read_b64_tr_b16 v[238:239], v194 offset:53632
	ds_read_b64_tr_b16 v[236:237], v194 offset:51456
	ds_read_b64_tr_b16 v[242:243], v194 offset:53664
	ds_read_b64_tr_b16 v[240:241], v194 offset:51488
	s_waitcnt lgkmcnt(10)
	v_mfma_f32_16x16x32_bf16 v[38:41], v[204:207], v[166:169], v[38:41]
	v_mfma_f32_16x16x32_bf16 v[34:37], v[204:207], v[174:177], v[34:37]
	s_waitcnt lgkmcnt(8)
	v_mfma_f32_16x16x32_bf16 v[46:49], v[208:211], v[166:169], v[46:49]
	v_mfma_f32_16x16x32_bf16 v[42:45], v[208:211], v[174:177], v[42:45]
	ds_read_b64_tr_b16 v[206:207], v194 offset:53696
	ds_read_b64_tr_b16 v[204:205], v194 offset:51520
	ds_read_b64_tr_b16 v[210:211], v194 offset:53728
	ds_read_b64_tr_b16 v[208:209], v194 offset:51552
	s_waitcnt lgkmcnt(10)
	v_mfma_f32_16x16x32_bf16 v[54:57], v[228:231], v[166:169], v[54:57]
	v_mfma_f32_16x16x32_bf16 v[50:53], v[228:231], v[174:177], v[50:53]
	s_waitcnt lgkmcnt(8)
	v_mfma_f32_16x16x32_bf16 v[62:65], v[232:235], v[166:169], v[62:65]
	v_mfma_f32_16x16x32_bf16 v[58:61], v[232:235], v[174:177], v[58:61]
	ds_read_b64_tr_b16 v[230:231], v194 offset:53760
	ds_read_b64_tr_b16 v[228:229], v194 offset:51584
	ds_read_b64_tr_b16 v[234:235], v194 offset:53792
	ds_read_b64_tr_b16 v[232:233], v194 offset:51616
	s_waitcnt lgkmcnt(10)
	v_mfma_f32_16x16x32_bf16 v[70:73], v[236:239], v[166:169], v[70:73]
	v_mfma_f32_16x16x32_bf16 v[66:69], v[236:239], v[174:177], v[66:69]
	s_waitcnt lgkmcnt(8)
	v_mfma_f32_16x16x32_bf16 v[78:81], v[240:243], v[166:169], v[78:81]
	v_mfma_f32_16x16x32_bf16 v[74:77], v[240:243], v[174:177], v[74:77]
	ds_read_b64_tr_b16 v[238:239], v194 offset:53824
	ds_read_b64_tr_b16 v[236:237], v194 offset:51648
	ds_read_b64_tr_b16 v[242:243], v194 offset:53856
	ds_read_b64_tr_b16 v[240:241], v194 offset:51680
	s_waitcnt lgkmcnt(10)
	v_mfma_f32_16x16x32_bf16 v[86:89], v[204:207], v[166:169], v[86:89]
	v_mfma_f32_16x16x32_bf16 v[82:85], v[204:207], v[174:177], v[82:85]
	s_waitcnt lgkmcnt(8)
	v_mfma_f32_16x16x32_bf16 v[94:97], v[208:211], v[166:169], v[94:97]
	v_mfma_f32_16x16x32_bf16 v[90:93], v[208:211], v[174:177], v[90:93]
	s_waitcnt lgkmcnt(6)
	v_mfma_f32_16x16x32_bf16 v[102:105], v[228:231], v[166:169], v[102:105]
	v_mfma_f32_16x16x32_bf16 v[98:101], v[228:231], v[174:177], v[98:101]
	s_waitcnt lgkmcnt(4)
	v_mfma_f32_16x16x32_bf16 v[110:113], v[232:235], v[166:169], v[110:113]
	v_mfma_f32_16x16x32_bf16 v[106:109], v[232:235], v[174:177], v[106:109]
	s_waitcnt lgkmcnt(2)
	v_mfma_f32_16x16x32_bf16 v[118:121], v[236:239], v[166:169], v[118:121]
	v_mfma_f32_16x16x32_bf16 v[114:117], v[236:239], v[174:177], v[114:117]
	s_waitcnt lgkmcnt(0)
	v_mfma_f32_16x16x32_bf16 v[126:129], v[240:243], v[166:169], v[126:129]
	v_mfma_f32_16x16x32_bf16 v[122:125], v[240:243], v[174:177], v[122:125]
	ds_read_b128 v[204:207], v218
	s_waitcnt lgkmcnt(0)
	v_pk_mul_f32 v[8:9], v[8:9], v[206:207]
	v_pk_mul_f32 v[6:7], v[6:7], v[204:205]
	v_pk_mul_f32 v[4:5], v[4:5], v[206:207]
	v_pk_mul_f32 v[2:3], v[2:3], v[204:205]
	ds_read_b128 v[204:207], v218 offset:64
	s_waitcnt lgkmcnt(0)
	v_pk_mul_f32 v[16:17], v[16:17], v[206:207]
	v_pk_mul_f32 v[14:15], v[14:15], v[204:205]
	v_pk_mul_f32 v[12:13], v[12:13], v[206:207]
	v_pk_mul_f32 v[10:11], v[10:11], v[204:205]
	ds_read_b128 v[204:207], v218 offset:128
	s_waitcnt lgkmcnt(0)
	v_pk_mul_f32 v[24:25], v[24:25], v[206:207]
	v_pk_mul_f32 v[22:23], v[22:23], v[204:205]
	v_pk_mul_f32 v[20:21], v[20:21], v[206:207]
	v_pk_mul_f32 v[18:19], v[18:19], v[204:205]
	ds_read_b128 v[204:207], v218 offset:192
	s_waitcnt lgkmcnt(0)
	v_pk_mul_f32 v[32:33], v[32:33], v[206:207]
	v_pk_mul_f32 v[30:31], v[30:31], v[204:205]
	v_pk_mul_f32 v[28:29], v[28:29], v[206:207]
	v_pk_mul_f32 v[26:27], v[26:27], v[204:205]
	ds_read_b128 v[204:207], v218 offset:256
	s_waitcnt lgkmcnt(0)
; #define LAS __attribute__((address_space(3)))
; __device__ __forceinline__ unsigned cvt2(float a, float b) { f32x2s v = {a, b}; bf16x2_t r = __builtin_convertvector(v, bf16x2_t); return __builtin_bit_cast(unsigned, r); }
; #define SC_BAR() do { asm volatile("s_waitcnt lgkmcnt(0)" ::: "memory"); __builtin_amdgcn_s_barrier(); asm volatile("" ::: "memory"); } while (0)
; template <bool GLA>
; __device__ __forceinline__ void scan_item2(LAS unsigned char* lds, const bf16* Qd, const bf16* Kd, const bf16* V, bf16* O, const float* EG, int ldqk, int ldv, int b, int h, int dvs, float e_const, int tid) {
;     ...
;             for (int t = 0; t < 16; ++t) { if (GLA) { const f32x4 e4 = *(const LAS f32x4*)(lds + SC_EI + (16 * t + 4 * fq) * 4); st[t][0] = st[t][0] * e4; st[t][1] = st[t][1] * e4; } else { st[t][0] = st[t][0] * e_const; st[t][1] = st[t][1] * e_const; } }
;             SC_BAR();
; #pragma unroll
;             for (int ks = 0; ks < 2; ++ks) { bf16x8s ap[4];
; #pragma unroll
;                 for (int ti = 0; ti < 4; ++ti) ap[ti] = *(const LAS bf16x8s*)(lds + SC_PI + (16 * ti + fr) * SC_PS + (32 * ks + 8 * fq) * 2);
; #pragma unroll
;                 for (int ti = 0; ti < 4; ++ti)
; #pragma unroll
;                     for (int ct = 0; ct < 2; ++ct) oa[ti][ct] = __builtin_amdgcn_mfma_f32_16x16x32_bf16(bv[ks][ct], ap[ti], oa[ti][ct], 0, 0, 0); }
; #pragma unroll
;             for (int ti = 0; ti < 4; ++ti)
; #pragma unroll
;                 for (int ct = 0; ct < 2; ++ct) { v2u ow; ow.x = cvt2(oa[ti][ct][0], oa[ti][ct][1]); ow.y = cvt2(oa[ti][ct][2], oa[ti][ct][3]);
;                     *(v2u*)((char*)(obase + ((size_t)c * 64 + 16 * ti) * ldv + 16 * ct) + ooff) = ow; }
;         }
	v_pk_mul_f32 v[40:41], v[40:41], v[206:207]
	v_pk_mul_f32 v[38:39], v[38:39], v[204:205]
	v_pk_mul_f32 v[36:37], v[36:37], v[206:207]
	v_pk_mul_f32 v[34:35], v[34:35], v[204:205]
	ds_read_b128 v[204:207], v218 offset:320
	s_waitcnt lgkmcnt(0)
	v_pk_mul_f32 v[48:49], v[48:49], v[206:207]
	v_pk_mul_f32 v[46:47], v[46:47], v[204:205]
	v_pk_mul_f32 v[44:45], v[44:45], v[206:207]
	v_pk_mul_f32 v[42:43], v[42:43], v[204:205]
	ds_read_b128 v[204:207], v218 offset:384
	s_waitcnt lgkmcnt(0)
	v_pk_mul_f32 v[56:57], v[56:57], v[206:207]
	v_pk_mul_f32 v[54:55], v[54:55], v[204:205]
	v_pk_mul_f32 v[52:53], v[52:53], v[206:207]
	v_pk_mul_f32 v[50:51], v[50:51], v[204:205]
	ds_read_b128 v[204:207], v218 offset:448
	s_waitcnt lgkmcnt(0)
	v_pk_mul_f32 v[64:65], v[64:65], v[206:207]
	v_pk_mul_f32 v[62:63], v[62:63], v[204:205]
	v_pk_mul_f32 v[60:61], v[60:61], v[206:207]
	v_pk_mul_f32 v[58:59], v[58:59], v[204:205]
	ds_read_b128 v[204:207], v218 offset:512
	s_waitcnt lgkmcnt(0)
	v_pk_mul_f32 v[72:73], v[72:73], v[206:207]
	v_pk_mul_f32 v[70:71], v[70:71], v[204:205]
	v_pk_mul_f32 v[68:69], v[68:69], v[206:207]
	v_pk_mul_f32 v[66:67], v[66:67], v[204:205]
	ds_read_b128 v[204:207], v218 offset:576
	s_waitcnt lgkmcnt(0)
	v_pk_mul_f32 v[80:81], v[80:81], v[206:207]
	v_pk_mul_f32 v[78:79], v[78:79], v[204:205]
	v_pk_mul_f32 v[76:77], v[76:77], v[206:207]
	v_pk_mul_f32 v[74:75], v[74:75], v[204:205]
	ds_read_b128 v[204:207], v218 offset:640
	s_waitcnt lgkmcnt(0)
	v_pk_mul_f32 v[88:89], v[88:89], v[206:207]
	v_pk_mul_f32 v[86:87], v[86:87], v[204:205]
	v_pk_mul_f32 v[84:85], v[84:85], v[206:207]
	v_pk_mul_f32 v[82:83], v[82:83], v[204:205]
	ds_read_b128 v[204:207], v218 offset:704
	s_waitcnt lgkmcnt(0)
	v_pk_mul_f32 v[96:97], v[96:97], v[206:207]
	v_pk_mul_f32 v[94:95], v[94:95], v[204:205]
	v_pk_mul_f32 v[92:93], v[92:93], v[206:207]
	v_pk_mul_f32 v[90:91], v[90:91], v[204:205]
	ds_read_b128 v[204:207], v218 offset:768
	s_waitcnt lgkmcnt(0)
	v_pk_mul_f32 v[104:105], v[104:105], v[206:207]
	v_pk_mul_f32 v[102:103], v[102:103], v[204:205]
	v_pk_mul_f32 v[100:101], v[100:101], v[206:207]
	v_pk_mul_f32 v[98:99], v[98:99], v[204:205]
	ds_read_b128 v[204:207], v218 offset:832
	s_waitcnt lgkmcnt(0)
	v_pk_mul_f32 v[112:113], v[112:113], v[206:207]
	v_pk_mul_f32 v[110:111], v[110:111], v[204:205]
	v_pk_mul_f32 v[108:109], v[108:109], v[206:207]
	v_pk_mul_f32 v[106:107], v[106:107], v[204:205]
	ds_read_b128 v[204:207], v218 offset:896
	s_waitcnt lgkmcnt(0)
	v_pk_mul_f32 v[120:121], v[120:121], v[206:207]
	v_pk_mul_f32 v[118:119], v[118:119], v[204:205]
	v_pk_mul_f32 v[116:117], v[116:117], v[206:207]
	v_pk_mul_f32 v[114:115], v[114:115], v[204:205]
	ds_read_b128 v[204:207], v218 offset:960
	s_waitcnt lgkmcnt(0)
	s_barrier
	s_waitcnt lgkmcnt(0)
	v_pk_mul_f32 v[128:129], v[128:129], v[206:207]
	v_pk_mul_f32 v[126:127], v[126:127], v[204:205]
	v_pk_mul_f32 v[124:125], v[124:125], v[206:207]
	v_pk_mul_f32 v[122:123], v[122:123], v[204:205]
	ds_read_b128 v[204:207], v219
	ds_read_b128 v[208:211], v219 offset:2560
	ds_read_b128 v[228:231], v219 offset:5120
	ds_read_b128 v[232:235], v219 offset:7680
	s_waitcnt lgkmcnt(3)
	v_mfma_f32_16x16x32_bf16 v[130:133], v[162:165], v[204:207], v[130:133]
	v_mfma_f32_16x16x32_bf16 v[158:161], v[170:173], v[204:207], v[158:161]
	s_waitcnt lgkmcnt(2)
	v_mfma_f32_16x16x32_bf16 v[134:137], v[162:165], v[208:211], v[134:137]
	v_mfma_f32_16x16x32_bf16 v[154:157], v[170:173], v[208:211], v[154:157]
	s_waitcnt lgkmcnt(1)
	v_mfma_f32_16x16x32_bf16 v[138:141], v[162:165], v[228:231], v[138:141]
	v_mfma_f32_16x16x32_bf16 v[150:153], v[170:173], v[228:231], v[150:153]
	s_waitcnt lgkmcnt(0)
	v_mfma_f32_16x16x32_bf16 v[142:145], v[162:165], v[232:235], v[142:145]
	v_mfma_f32_16x16x32_bf16 v[146:149], v[170:173], v[232:235], v[146:149]
	ds_read_b128 v[162:165], v219 offset:64
	ds_read_b128 v[170:173], v219 offset:2624
	ds_read_b128 v[204:207], v219 offset:5184
	ds_read_b128 v[208:211], v219 offset:7744
	s_waitcnt lgkmcnt(3)
	v_mfma_f32_16x16x32_bf16 v[130:133], v[166:169], v[162:165], v[130:133]
	v_mfma_f32_16x16x32_bf16 v[158:161], v[174:177], v[162:165], v[158:161]
	v_lshl_add_u64 v[162:163], v[190:191], 0, s[10:11]
	s_nop 5
	v_cvt_pk_bf16_f32 v130, v130, v131
	v_cvt_pk_bf16_f32 v131, v132, v133
	s_waitcnt lgkmcnt(2)
	v_mfma_f32_16x16x32_bf16 v[134:137], v[166:169], v[170:173], v[134:137]
	v_add_co_u32_e32 v132, vcc, s45, v162
	s_add_u32 s10, s10, 0x40000
	v_mfma_f32_16x16x32_bf16 v[154:157], v[174:177], v[170:173], v[154:157]
	v_addc_co_u32_e32 v133, vcc, 0, v163, vcc
	global_store_dwordx2 v[132:133], v[130:131], off
	v_cvt_pk_bf16_f32 v130, v158, v159
	v_cvt_pk_bf16_f32 v131, v160, v161
	s_waitcnt lgkmcnt(1)
	v_mfma_f32_16x16x32_bf16 v[138:141], v[166:169], v[204:207], v[138:141]
	global_store_dwordx2 v[132:133], v[130:131], off offset:32
	v_add_co_u32_e32 v132, vcc, s46, v162
	v_mfma_f32_16x16x32_bf16 v[150:153], v[174:177], v[204:207], v[150:153]
	v_cvt_pk_bf16_f32 v130, v134, v135
	v_cvt_pk_bf16_f32 v131, v136, v137
	v_addc_co_u32_e32 v133, vcc, 0, v163, vcc
	global_store_dwordx2 v[132:133], v[130:131], off
	v_cvt_pk_bf16_f32 v130, v154, v155
	v_cvt_pk_bf16_f32 v131, v156, v157
	s_waitcnt lgkmcnt(0)
	v_mfma_f32_16x16x32_bf16 v[142:145], v[166:169], v[208:211], v[142:145]
	global_store_dwordx2 v[132:133], v[130:131], off offset:32
	v_add_co_u32_e32 v132, vcc, s47, v162
	v_mfma_f32_16x16x32_bf16 v[146:149], v[174:177], v[208:211], v[146:149]
	v_cvt_pk_bf16_f32 v130, v138, v139
	v_cvt_pk_bf16_f32 v131, v140, v141
	v_addc_co_u32_e32 v133, vcc, 0, v163, vcc
	global_store_dwordx2 v[132:133], v[130:131], off
	v_cvt_pk_bf16_f32 v130, v150, v151
	v_cvt_pk_bf16_f32 v131, v152, v153
	global_store_dwordx2 v[132:133], v[130:131], off offset:32
	v_add_co_u32_e32 v132, vcc, s52, v162
	v_cvt_pk_bf16_f32 v130, v142, v143
	v_cvt_pk_bf16_f32 v131, v144, v145
	v_addc_co_u32_e32 v133, vcc, 0, v163, vcc
	s_addc_u32 s11, s11, 0
	global_store_dwordx2 v[132:133], v[130:131], off
	v_cvt_pk_bf16_f32 v130, v146, v147
	v_cvt_pk_bf16_f32 v131, v148, v149
	s_cmp_eq_u32 s10, 0x800000
	global_store_dwordx2 v[132:133], v[130:131], off offset:32
	s_cbranch_scc0 .LBB0_1911
	s_waitcnt lgkmcnt(0)
	s_barrier
	s_branch .LBB0_1907
